# up-GEMM conv epilogues: row shifts use DPP bound_ctrl so the 64 v_mov clears in front of them are gone (stacked on the peeled GEMM first iterations)
# speedup vs baseline: 1.0047x; 1.0005x over previous
.LBB0_2073:
	ds_read_b128 v[4:7], v180
	ds_read_b128 v[8:11], v180 offset:16
	ds_read_b128 v[12:15], v180 offset:2048
	ds_read_b128 v[16:19], v180 offset:2064
	s_ashr_i32 s1, s0, 31
	s_lshl_b64 s[2:3], s[0:1], 18
	s_add_u32 s16, s26, s2
	s_addc_u32 s17, s27, s3
	s_and_b64 s[2:3], s[44:45], exec
	s_cselect_b32 s3, s17, s19
	s_cselect_b32 s2, s16, s18
	v_lshl_add_u64 v[0:1], s[20:21], 0, v[130:131]
	s_mov_b64 s[20:21], 0x1080
	s_add_i32 s49, s29, 0xc000
	v_lshl_add_u64 v[2:3], v[0:1], 0, s[20:21]
	s_mov_b32 m0, s49
	s_mov_b64 s[20:21], 0x20880
	s_add_i32 s1, s29, 0xe000
	ds_read_b128 v[20:23], v179
	ds_read_b128 v[24:27], v179 offset:16
	ds_read_b128 v[28:31], v179 offset:2048
	ds_read_b128 v[32:35], v179 offset:2064
	ds_read_b128 v[36:39], v179 offset:4096
	ds_read_b128 v[40:43], v179 offset:4112
	ds_read_b128 v[44:47], v179 offset:6144
	ds_read_b128 v[48:51], v179 offset:6160
	global_load_lds_dwordx4 v[2:3], off
	v_lshl_add_u64 v[2:3], v[0:1], 0, s[20:21]
	s_mov_b32 m0, s1
	s_nop 0
	global_load_lds_dwordx4 v[2:3], off
	s_waitcnt lgkmcnt(8)
	s_barrier
	s_waitcnt lgkmcnt(0)
	s_setprio 1
	s_waitcnt lgkmcnt(0)
	v_mfma_f32_16x16x128_f8f6f4 v[68:71], v[4:11], v[20:27], 0
	v_mfma_f32_16x16x128_f8f6f4 v[72:75], v[12:19], v[20:27], 0
	v_mfma_f32_16x16x128_f8f6f4 v[76:79], v[4:11], v[28:35], 0
	v_mfma_f32_16x16x128_f8f6f4 v[80:83], v[12:19], v[28:35], 0
	v_mfma_f32_16x16x128_f8f6f4 v[84:87], v[4:11], v[36:43], 0
	v_mfma_f32_16x16x128_f8f6f4 v[88:91], v[12:19], v[36:43], 0
	v_mfma_f32_16x16x128_f8f6f4 v[92:95], v[4:11], v[44:51], 0
	v_mfma_f32_16x16x128_f8f6f4 v[96:99], v[12:19], v[44:51], 0
	s_setprio 0
	s_barrier
	v_lshl_add_u64 v[2:3], s[18:19], 0, v[128:129]
	s_add_i32 s47, s4, s28
	v_lshl_add_u64 v[100:101], v[2:3], 0, s[84:85]
	s_mov_b32 m0, s47
	s_mov_b64 s[18:19], 0x10100
	ds_read_b128 v[52:55], v181
	ds_read_b128 v[56:59], v181 offset:16
	ds_read_b128 v[60:63], v181 offset:2048
	ds_read_b128 v[64:67], v181 offset:2064
	global_load_lds_dwordx4 v[100:101], off
	v_lshl_add_u64 v[100:101], v[2:3], 0, s[18:19]
	s_add_i32 s18, s47, 0x2000
	s_mov_b32 m0, s18
	s_nop 0
	global_load_lds_dwordx4 v[100:101], off
	s_barrier
	s_waitcnt lgkmcnt(0)
	s_setprio 1
	s_waitcnt lgkmcnt(0)
	v_mfma_f32_16x16x128_f8f6f4 v[100:103], v[52:59], v[20:27], 0
	v_mfma_f32_16x16x128_f8f6f4 v[104:107], v[60:67], v[20:27], 0
	v_mfma_f32_16x16x128_f8f6f4 v[108:111], v[52:59], v[28:35], 0
	v_mfma_f32_16x16x128_f8f6f4 v[112:115], v[60:67], v[28:35], 0
	v_mfma_f32_16x16x128_f8f6f4 v[116:119], v[52:59], v[36:43], 0
	v_mfma_f32_16x16x128_f8f6f4 v[120:123], v[60:67], v[36:43], 0
	v_mfma_f32_16x16x128_f8f6f4 v[124:127], v[52:59], v[44:51], 0
	v_mfma_f32_16x16x128_f8f6f4 v[136:139], v[60:67], v[44:51], 0
	s_setprio 0
	s_mov_b32 m0, s29
	v_lshl_add_u64 v[132:133], v[0:1], 0, s[84:85]
	s_mov_b64 s[20:21], 0x1f900
	s_barrier
	ds_read_b128 v[20:23], v179 offset:16384
	ds_read_b128 v[24:27], v179 offset:16400
	ds_read_b128 v[28:31], v179 offset:18432
	ds_read_b128 v[32:35], v179 offset:18448
	ds_read_b128 v[36:39], v179 offset:20480
	ds_read_b128 v[40:43], v179 offset:20496
	ds_read_b128 v[44:47], v179 offset:22528
	ds_read_b128 v[48:51], v179 offset:22544
	global_load_lds_dwordx4 v[132:133], off
	v_lshl_add_u64 v[132:133], v[0:1], 0, s[20:21]
	s_mov_b32 m0, s33
	s_nop 0
	global_load_lds_dwordx4 v[132:133], off
	s_barrier
	s_waitcnt lgkmcnt(0)
	s_setprio 1
	s_waitcnt lgkmcnt(0)
	v_mfma_f32_16x16x128_f8f6f4 v[140:143], v[4:11], v[20:27], 0
	v_mfma_f32_16x16x128_f8f6f4 v[144:147], v[12:19], v[20:27], 0
	v_mfma_f32_16x16x128_f8f6f4 v[148:151], v[4:11], v[28:35], 0
	v_mfma_f32_16x16x128_f8f6f4 v[152:155], v[12:19], v[28:35], 0
	v_mfma_f32_16x16x128_f8f6f4 v[156:159], v[4:11], v[36:43], 0
	v_mfma_f32_16x16x128_f8f6f4 v[160:163], v[12:19], v[36:43], 0
	v_mfma_f32_16x16x128_f8f6f4 v[164:167], v[4:11], v[44:51], 0
	v_mfma_f32_16x16x128_f8f6f4 v[168:171], v[12:19], v[44:51], 0
	s_setprio 0
	s_barrier
	s_mov_b64 s[20:21], 0x20100
	s_add_i32 s19, s5, s28
	v_lshl_add_u64 v[4:5], v[2:3], 0, s[20:21]
	s_mov_b32 m0, s19
	s_mov_b64 s[20:21], 0x30100
	global_load_lds_dwordx4 v[4:5], off
	v_lshl_add_u64 v[4:5], v[2:3], 0, s[20:21]
	s_add_i32 s20, s19, 0x2000
	s_mov_b32 m0, s20
	s_nop 0
	global_load_lds_dwordx4 v[4:5], off
	s_waitcnt vmcnt(6)
	s_barrier
	s_setprio 1
	v_mfma_f32_16x16x128_f8f6f4 v[172:175], v[52:59], v[20:27], 0
	v_mfma_f32_16x16x128_f8f6f4 v[182:185], v[60:67], v[20:27], 0
	v_mfma_f32_16x16x128_f8f6f4 v[186:189], v[52:59], v[28:35], 0
	v_mfma_f32_16x16x128_f8f6f4 v[30:33], v[60:67], v[28:35], 0
	v_mfma_f32_16x16x128_f8f6f4 v[190:193], v[52:59], v[36:43], 0
	v_mfma_f32_16x16x128_f8f6f4 v[194:197], v[60:67], v[36:43], 0
	v_mfma_f32_16x16x128_f8f6f4 v[198:201], v[52:59], v[44:51], 0
	v_mfma_f32_16x16x128_f8f6f4 v[202:205], v[60:67], v[44:51], 0
	s_setprio 0
	s_add_i32 s48, 0, 0x18000
	v_add_u32_e32 v4, s48, v178
	s_barrier
	ds_read_b128 v[6:9], v4
	ds_read_b128 v[10:13], v4 offset:16
	ds_read_b128 v[14:17], v4 offset:2048
	ds_read_b128 v[18:21], v4 offset:2064
	s_mov_b64 s[44:45], 0x1100
	s_mov_b32 m0, s39
	v_lshl_add_u64 v[34:35], v[0:1], 0, s[44:45]
	s_mov_b64 s[44:45], 0x20900
	ds_read_b128 v[22:25], v179 offset:32768
	ds_read_b128 v[26:29], v179 offset:32784
	ds_read_b128 v[36:39], v179 offset:34816
	ds_read_b128 v[40:43], v179 offset:34832
	ds_read_b128 v[44:47], v179 offset:36864
	ds_read_b128 v[48:51], v179 offset:36880
	ds_read_b128 v[52:55], v179 offset:38912
	ds_read_b128 v[56:59], v179 offset:38928
	global_load_lds_dwordx4 v[34:35], off
	v_lshl_add_u64 v[34:35], v[0:1], 0, s[44:45]
	s_mov_b32 m0, s88
	s_nop 0
	global_load_lds_dwordx4 v[34:35], off
	s_waitcnt lgkmcnt(8)
	s_barrier
	s_waitcnt lgkmcnt(0)
	s_setprio 1
	s_waitcnt lgkmcnt(0)
	v_mfma_f32_16x16x128_f8f6f4 v[206:209], v[6:13], v[22:29], v[68:71]
	v_mfma_f32_16x16x128_f8f6f4 v[210:213], v[14:21], v[22:29], v[72:75]
	v_mfma_f32_16x16x128_f8f6f4 v[76:79], v[6:13], v[36:43], v[76:79]
	v_mfma_f32_16x16x128_f8f6f4 v[80:83], v[14:21], v[36:43], v[80:83]
	v_mfma_f32_16x16x128_f8f6f4 v[84:87], v[6:13], v[44:51], v[84:87]
	v_mfma_f32_16x16x128_f8f6f4 v[88:91], v[14:21], v[44:51], v[88:91]
	v_mfma_f32_16x16x128_f8f6f4 v[92:95], v[6:13], v[52:59], v[92:95]
	v_mfma_f32_16x16x128_f8f6f4 v[96:99], v[14:21], v[52:59], v[96:99]
	s_setprio 0
	s_barrier
	s_add_i32 s50, 0, 0x1c000
	s_add_i32 s48, s48, s28
	v_add_u32_e32 v34, s50, v178
	v_lshl_add_u64 v[132:133], v[2:3], 0, s[86:87]
	s_mov_b32 m0, s48
	s_mov_b64 s[44:45], 0x10180
	s_add_i32 s21, s48, 0x2000
	ds_read_b128 v[60:63], v34
	ds_read_b128 v[64:67], v34 offset:16
	ds_read_b128 v[68:71], v34 offset:2048
	ds_read_b128 v[72:75], v34 offset:2064
	global_load_lds_dwordx4 v[132:133], off
	v_lshl_add_u64 v[132:133], v[2:3], 0, s[44:45]
	s_mov_b32 m0, s21
	s_nop 0
	global_load_lds_dwordx4 v[132:133], off
	s_barrier
	s_waitcnt lgkmcnt(0)
	s_setprio 1
	s_waitcnt lgkmcnt(0)
	v_mfma_f32_16x16x128_f8f6f4 v[100:103], v[60:67], v[22:29], v[100:103]
	v_mfma_f32_16x16x128_f8f6f4 v[104:107], v[68:75], v[22:29], v[104:107]
	v_mfma_f32_16x16x128_f8f6f4 v[108:111], v[60:67], v[36:43], v[108:111]
	v_mfma_f32_16x16x128_f8f6f4 v[112:115], v[68:75], v[36:43], v[112:115]
	v_mfma_f32_16x16x128_f8f6f4 v[116:119], v[60:67], v[44:51], v[116:119]
	v_mfma_f32_16x16x128_f8f6f4 v[120:123], v[68:75], v[44:51], v[120:123]
	v_mfma_f32_16x16x128_f8f6f4 v[124:127], v[60:67], v[52:59], v[124:127]
	v_mfma_f32_16x16x128_f8f6f4 v[136:139], v[68:75], v[52:59], v[136:139]
	s_setprio 0
	s_mov_b32 m0, s75
	v_lshl_add_u64 v[132:133], v[0:1], 0, s[86:87]
	s_mov_b64 s[44:45], 0x1f980
	s_barrier
	ds_read_b128 v[22:25], v179 offset:49152
	ds_read_b128 v[26:29], v179 offset:49168
	ds_read_b128 v[36:39], v179 offset:51200
	ds_read_b128 v[40:43], v179 offset:51216
	ds_read_b128 v[44:47], v179 offset:53248
	ds_read_b128 v[48:51], v179 offset:53264
	ds_read_b128 v[52:55], v179 offset:55296
	ds_read_b128 v[56:59], v179 offset:55312
	global_load_lds_dwordx4 v[132:133], off
	v_lshl_add_u64 v[132:133], v[0:1], 0, s[44:45]
	s_mov_b32 m0, s22
	s_nop 0
	global_load_lds_dwordx4 v[132:133], off
	s_barrier
	s_waitcnt lgkmcnt(0)
	s_setprio 1
	s_waitcnt lgkmcnt(0)
	v_mfma_f32_16x16x128_f8f6f4 v[140:143], v[6:13], v[22:29], v[140:143]
	v_mfma_f32_16x16x128_f8f6f4 v[144:147], v[14:21], v[22:29], v[144:147]
	v_mfma_f32_16x16x128_f8f6f4 v[148:151], v[6:13], v[36:43], v[148:151]
	v_mfma_f32_16x16x128_f8f6f4 v[152:155], v[14:21], v[36:43], v[152:155]
	v_mfma_f32_16x16x128_f8f6f4 v[156:159], v[6:13], v[44:51], v[156:159]
	v_mfma_f32_16x16x128_f8f6f4 v[160:163], v[14:21], v[44:51], v[160:163]
	v_mfma_f32_16x16x128_f8f6f4 v[164:167], v[6:13], v[52:59], v[164:167]
	v_mfma_f32_16x16x128_f8f6f4 v[168:171], v[14:21], v[52:59], v[168:171]
	s_setprio 0
	s_barrier
	s_mov_b64 s[44:45], 0x20180
	v_lshl_add_u64 v[6:7], v[2:3], 0, s[44:45]
	s_add_i32 s44, s50, s28
	s_mov_b32 m0, s44
	s_mov_b64 s[50:51], 0x30180
	s_add_i32 s45, s44, 0x2000
	global_load_lds_dwordx4 v[6:7], off
	v_lshl_add_u64 v[6:7], v[2:3], 0, s[50:51]
	s_mov_b32 m0, s45
	s_nop 0
	global_load_lds_dwordx4 v[6:7], off
	s_waitcnt vmcnt(6)
	s_barrier
	s_setprio 1
	v_mfma_f32_16x16x128_f8f6f4 v[172:175], v[60:67], v[22:29], v[172:175]
	v_mfma_f32_16x16x128_f8f6f4 v[182:185], v[68:75], v[22:29], v[182:185]
	v_mfma_f32_16x16x128_f8f6f4 v[186:189], v[60:67], v[36:43], v[186:189]
	v_mfma_f32_16x16x128_f8f6f4 v[30:33], v[68:75], v[36:43], v[30:33]
	v_mfma_f32_16x16x128_f8f6f4 v[190:193], v[60:67], v[44:51], v[190:193]
	v_mfma_f32_16x16x128_f8f6f4 v[194:197], v[68:75], v[44:51], v[194:197]
	v_mfma_f32_16x16x128_f8f6f4 v[198:201], v[60:67], v[52:59], v[198:201]
	v_mfma_f32_16x16x128_f8f6f4 v[202:205], v[68:75], v[52:59], v[202:205]
	s_setprio 0
	s_barrier
	ds_read_b128 v[6:9], v180
	ds_read_b128 v[10:13], v180 offset:16
	ds_read_b128 v[14:17], v180 offset:2048
	ds_read_b128 v[18:21], v180 offset:2064
	s_mov_b64 s[50:51], 0x1180
	s_mov_b32 m0, s49
	v_lshl_add_u64 v[60:61], v[0:1], 0, s[50:51]
	s_mov_b64 s[50:51], 0x20980
	ds_read_b128 v[22:25], v179
	ds_read_b128 v[26:29], v179 offset:16
	ds_read_b128 v[36:39], v179 offset:2048
	ds_read_b128 v[40:43], v179 offset:2064
	ds_read_b128 v[44:47], v179 offset:4096
	ds_read_b128 v[48:51], v179 offset:4112
	ds_read_b128 v[52:55], v179 offset:6144
	ds_read_b128 v[56:59], v179 offset:6160
	global_load_lds_dwordx4 v[60:61], off
	v_lshl_add_u64 v[60:61], v[0:1], 0, s[50:51]
	s_mov_b32 m0, s1
	s_nop 0
	global_load_lds_dwordx4 v[60:61], off
	s_waitcnt lgkmcnt(8)
	s_barrier
	s_waitcnt lgkmcnt(0)
	s_setprio 1
	s_waitcnt lgkmcnt(0)
	v_mfma_f32_16x16x128_f8f6f4 v[206:209], v[6:13], v[22:29], v[206:209]
	v_mfma_f32_16x16x128_f8f6f4 v[210:213], v[14:21], v[22:29], v[210:213]
	v_mfma_f32_16x16x128_f8f6f4 v[76:79], v[6:13], v[36:43], v[76:79]
	v_mfma_f32_16x16x128_f8f6f4 v[80:83], v[14:21], v[36:43], v[80:83]
	v_mfma_f32_16x16x128_f8f6f4 v[84:87], v[6:13], v[44:51], v[84:87]
	v_mfma_f32_16x16x128_f8f6f4 v[88:91], v[14:21], v[44:51], v[88:91]
	v_mfma_f32_16x16x128_f8f6f4 v[92:95], v[6:13], v[52:59], v[92:95]
	v_mfma_f32_16x16x128_f8f6f4 v[96:99], v[14:21], v[52:59], v[96:99]
	s_setprio 0
	s_barrier
	s_mov_b32 m0, s47
	v_lshl_add_u64 v[132:133], v[2:3], 0, s[90:91]
	s_mov_b64 s[50:51], 0x10200
	ds_read_b128 v[60:63], v181
	ds_read_b128 v[64:67], v181 offset:16
	ds_read_b128 v[68:71], v181 offset:2048
	ds_read_b128 v[72:75], v181 offset:2064
	global_load_lds_dwordx4 v[132:133], off
	v_lshl_add_u64 v[132:133], v[2:3], 0, s[50:51]
	s_mov_b32 m0, s18
	s_nop 0
	global_load_lds_dwordx4 v[132:133], off
	s_barrier
	s_waitcnt lgkmcnt(0)
	s_setprio 1
	s_waitcnt lgkmcnt(0)
	v_mfma_f32_16x16x128_f8f6f4 v[100:103], v[60:67], v[22:29], v[100:103]
	v_mfma_f32_16x16x128_f8f6f4 v[104:107], v[68:75], v[22:29], v[104:107]
	v_mfma_f32_16x16x128_f8f6f4 v[108:111], v[60:67], v[36:43], v[108:111]
	v_mfma_f32_16x16x128_f8f6f4 v[112:115], v[68:75], v[36:43], v[112:115]
	v_mfma_f32_16x16x128_f8f6f4 v[116:119], v[60:67], v[44:51], v[116:119]
	v_mfma_f32_16x16x128_f8f6f4 v[120:123], v[68:75], v[44:51], v[120:123]
	v_mfma_f32_16x16x128_f8f6f4 v[124:127], v[60:67], v[52:59], v[124:127]
	v_mfma_f32_16x16x128_f8f6f4 v[136:139], v[68:75], v[52:59], v[136:139]
	s_setprio 0
	s_mov_b32 m0, s29
	v_lshl_add_u64 v[132:133], v[0:1], 0, s[90:91]
	s_mov_b64 s[50:51], 0x1fa00
	s_barrier
	ds_read_b128 v[22:25], v179 offset:16384
	ds_read_b128 v[26:29], v179 offset:16400
	ds_read_b128 v[36:39], v179 offset:18432
	ds_read_b128 v[40:43], v179 offset:18448
	ds_read_b128 v[44:47], v179 offset:20480
	ds_read_b128 v[48:51], v179 offset:20496
	ds_read_b128 v[52:55], v179 offset:22528
	ds_read_b128 v[56:59], v179 offset:22544
	global_load_lds_dwordx4 v[132:133], off
	v_lshl_add_u64 v[132:133], v[0:1], 0, s[50:51]
	s_mov_b32 m0, s33
	s_nop 0
	global_load_lds_dwordx4 v[132:133], off
	s_barrier
	s_waitcnt lgkmcnt(0)
	s_setprio 1
	s_waitcnt lgkmcnt(0)
	v_mfma_f32_16x16x128_f8f6f4 v[140:143], v[6:13], v[22:29], v[140:143]
	v_mfma_f32_16x16x128_f8f6f4 v[144:147], v[14:21], v[22:29], v[144:147]
	v_mfma_f32_16x16x128_f8f6f4 v[148:151], v[6:13], v[36:43], v[148:151]
	v_mfma_f32_16x16x128_f8f6f4 v[152:155], v[14:21], v[36:43], v[152:155]
	v_mfma_f32_16x16x128_f8f6f4 v[156:159], v[6:13], v[44:51], v[156:159]
	v_mfma_f32_16x16x128_f8f6f4 v[160:163], v[14:21], v[44:51], v[160:163]
	v_mfma_f32_16x16x128_f8f6f4 v[164:167], v[6:13], v[52:59], v[164:167]
	v_mfma_f32_16x16x128_f8f6f4 v[168:171], v[14:21], v[52:59], v[168:171]
	s_setprio 0
	s_barrier
	s_mov_b64 s[50:51], 0x20200
	s_mov_b32 m0, s19
	v_lshl_add_u64 v[6:7], v[2:3], 0, s[50:51]
	s_mov_b64 s[50:51], 0x30200
	global_load_lds_dwordx4 v[6:7], off
	v_lshl_add_u64 v[6:7], v[2:3], 0, s[50:51]
	s_mov_b32 m0, s20
	s_nop 0
	global_load_lds_dwordx4 v[6:7], off
	s_waitcnt vmcnt(6)
	s_barrier
	s_setprio 1
	v_mfma_f32_16x16x128_f8f6f4 v[172:175], v[60:67], v[22:29], v[172:175]
	v_mfma_f32_16x16x128_f8f6f4 v[182:185], v[68:75], v[22:29], v[182:185]
	v_mfma_f32_16x16x128_f8f6f4 v[186:189], v[60:67], v[36:43], v[186:189]
	v_mfma_f32_16x16x128_f8f6f4 v[30:33], v[68:75], v[36:43], v[30:33]
	v_mfma_f32_16x16x128_f8f6f4 v[190:193], v[60:67], v[44:51], v[190:193]
	v_mfma_f32_16x16x128_f8f6f4 v[194:197], v[68:75], v[44:51], v[194:197]
	v_mfma_f32_16x16x128_f8f6f4 v[198:201], v[60:67], v[52:59], v[198:201]
	v_mfma_f32_16x16x128_f8f6f4 v[202:205], v[68:75], v[52:59], v[202:205]
	s_setprio 0
	s_barrier
	ds_read_b128 v[6:9], v4
	ds_read_b128 v[10:13], v4 offset:16
	ds_read_b128 v[14:17], v4 offset:2048
	ds_read_b128 v[18:21], v4 offset:2064
	s_mov_b64 s[50:51], 0x1200
	s_mov_b32 m0, s39
	v_lshl_add_u64 v[60:61], v[0:1], 0, s[50:51]
	s_mov_b64 s[50:51], 0x20a00
	ds_read_b128 v[22:25], v179 offset:32768
	ds_read_b128 v[26:29], v179 offset:32784
	ds_read_b128 v[36:39], v179 offset:34816
	ds_read_b128 v[40:43], v179 offset:34832
	ds_read_b128 v[44:47], v179 offset:36864
	ds_read_b128 v[48:51], v179 offset:36880
	ds_read_b128 v[52:55], v179 offset:38912
	ds_read_b128 v[56:59], v179 offset:38928
	global_load_lds_dwordx4 v[60:61], off
	v_lshl_add_u64 v[60:61], v[0:1], 0, s[50:51]
	s_mov_b32 m0, s88
	s_nop 0
	global_load_lds_dwordx4 v[60:61], off
	s_waitcnt lgkmcnt(8)
	s_barrier
	s_waitcnt lgkmcnt(0)
	s_setprio 1
	s_waitcnt lgkmcnt(0)
	v_mfma_f32_16x16x128_f8f6f4 v[206:209], v[6:13], v[22:29], v[206:209]
	v_mfma_f32_16x16x128_f8f6f4 v[210:213], v[14:21], v[22:29], v[210:213]
	v_mfma_f32_16x16x128_f8f6f4 v[76:79], v[6:13], v[36:43], v[76:79]
	v_mfma_f32_16x16x128_f8f6f4 v[80:83], v[14:21], v[36:43], v[80:83]
	v_mfma_f32_16x16x128_f8f6f4 v[84:87], v[6:13], v[44:51], v[84:87]
	v_mfma_f32_16x16x128_f8f6f4 v[88:91], v[14:21], v[44:51], v[88:91]
	v_mfma_f32_16x16x128_f8f6f4 v[92:95], v[6:13], v[52:59], v[92:95]
	v_mfma_f32_16x16x128_f8f6f4 v[96:99], v[14:21], v[52:59], v[96:99]
	s_setprio 0
	s_barrier
	s_mov_b32 m0, s48
	v_lshl_add_u64 v[132:133], v[2:3], 0, s[92:93]
	s_mov_b64 s[50:51], 0x10280
	ds_read_b128 v[60:63], v34
	ds_read_b128 v[64:67], v34 offset:16
	ds_read_b128 v[68:71], v34 offset:2048
	ds_read_b128 v[72:75], v34 offset:2064
	global_load_lds_dwordx4 v[132:133], off
	v_lshl_add_u64 v[132:133], v[2:3], 0, s[50:51]
	s_mov_b32 m0, s21
	s_nop 0
	global_load_lds_dwordx4 v[132:133], off
	s_barrier
	s_waitcnt lgkmcnt(0)
	s_setprio 1
	s_waitcnt lgkmcnt(0)
	v_mfma_f32_16x16x128_f8f6f4 v[100:103], v[60:67], v[22:29], v[100:103]
	v_mfma_f32_16x16x128_f8f6f4 v[104:107], v[68:75], v[22:29], v[104:107]
	v_mfma_f32_16x16x128_f8f6f4 v[108:111], v[60:67], v[36:43], v[108:111]
	v_mfma_f32_16x16x128_f8f6f4 v[112:115], v[68:75], v[36:43], v[112:115]
	v_mfma_f32_16x16x128_f8f6f4 v[116:119], v[60:67], v[44:51], v[116:119]
	v_mfma_f32_16x16x128_f8f6f4 v[120:123], v[68:75], v[44:51], v[120:123]
	v_mfma_f32_16x16x128_f8f6f4 v[124:127], v[60:67], v[52:59], v[124:127]
	v_mfma_f32_16x16x128_f8f6f4 v[136:139], v[68:75], v[52:59], v[136:139]
	s_setprio 0
	s_mov_b32 m0, s75
	v_lshl_add_u64 v[132:133], v[0:1], 0, s[92:93]
	s_mov_b64 s[50:51], 0x1fa80
	s_barrier
	ds_read_b128 v[22:25], v179 offset:49152
	ds_read_b128 v[26:29], v179 offset:49168
	ds_read_b128 v[36:39], v179 offset:51200
	ds_read_b128 v[40:43], v179 offset:51216
	ds_read_b128 v[44:47], v179 offset:53248
	ds_read_b128 v[48:51], v179 offset:53264
	ds_read_b128 v[52:55], v179 offset:55296
	ds_read_b128 v[56:59], v179 offset:55312
	global_load_lds_dwordx4 v[132:133], off
	v_lshl_add_u64 v[132:133], v[0:1], 0, s[50:51]
	s_mov_b32 m0, s22
	s_nop 0
	global_load_lds_dwordx4 v[132:133], off
	s_barrier
	s_waitcnt lgkmcnt(0)
	s_setprio 1
	s_waitcnt lgkmcnt(0)
	v_mfma_f32_16x16x128_f8f6f4 v[140:143], v[6:13], v[22:29], v[140:143]
	v_mfma_f32_16x16x128_f8f6f4 v[144:147], v[14:21], v[22:29], v[144:147]
	v_mfma_f32_16x16x128_f8f6f4 v[148:151], v[6:13], v[36:43], v[148:151]
	v_mfma_f32_16x16x128_f8f6f4 v[152:155], v[14:21], v[36:43], v[152:155]
	v_mfma_f32_16x16x128_f8f6f4 v[156:159], v[6:13], v[44:51], v[156:159]
	v_mfma_f32_16x16x128_f8f6f4 v[160:163], v[14:21], v[44:51], v[160:163]
	v_mfma_f32_16x16x128_f8f6f4 v[164:167], v[6:13], v[52:59], v[164:167]
	v_mfma_f32_16x16x128_f8f6f4 v[168:171], v[14:21], v[52:59], v[168:171]
	s_setprio 0
	s_barrier
	s_mov_b64 s[50:51], 0x20280
	s_mov_b32 m0, s44
	v_lshl_add_u64 v[6:7], v[2:3], 0, s[50:51]
	s_mov_b64 s[50:51], 0x30280
	global_load_lds_dwordx4 v[6:7], off
	v_lshl_add_u64 v[6:7], v[2:3], 0, s[50:51]
	s_mov_b32 m0, s45
	s_nop 0
	global_load_lds_dwordx4 v[6:7], off
	s_waitcnt vmcnt(6)
	s_barrier
	s_setprio 1
	v_mfma_f32_16x16x128_f8f6f4 v[172:175], v[60:67], v[22:29], v[172:175]
	v_mfma_f32_16x16x128_f8f6f4 v[182:185], v[68:75], v[22:29], v[182:185]
	v_mfma_f32_16x16x128_f8f6f4 v[186:189], v[60:67], v[36:43], v[186:189]
	v_mfma_f32_16x16x128_f8f6f4 v[30:33], v[68:75], v[36:43], v[30:33]
	v_mfma_f32_16x16x128_f8f6f4 v[190:193], v[60:67], v[44:51], v[190:193]
	v_mfma_f32_16x16x128_f8f6f4 v[194:197], v[68:75], v[44:51], v[194:197]
	v_mfma_f32_16x16x128_f8f6f4 v[198:201], v[60:67], v[52:59], v[198:201]
	v_mfma_f32_16x16x128_f8f6f4 v[202:205], v[68:75], v[52:59], v[202:205]
	s_setprio 0
	s_barrier
	ds_read_b128 v[6:9], v180
	ds_read_b128 v[10:13], v180 offset:16
	ds_read_b128 v[14:17], v180 offset:2048
	ds_read_b128 v[18:21], v180 offset:2064
	s_mov_b64 s[50:51], 0x1280
	s_mov_b32 m0, s49
	v_lshl_add_u64 v[60:61], v[0:1], 0, s[50:51]
	s_mov_b64 s[50:51], 0x20a80
	ds_read_b128 v[22:25], v179
	ds_read_b128 v[26:29], v179 offset:16
	ds_read_b128 v[36:39], v179 offset:2048
	ds_read_b128 v[40:43], v179 offset:2064
	ds_read_b128 v[44:47], v179 offset:4096
	ds_read_b128 v[48:51], v179 offset:4112
	ds_read_b128 v[52:55], v179 offset:6144
	ds_read_b128 v[56:59], v179 offset:6160
	global_load_lds_dwordx4 v[60:61], off
	v_lshl_add_u64 v[60:61], v[0:1], 0, s[50:51]
	s_mov_b32 m0, s1
	s_nop 0
	global_load_lds_dwordx4 v[60:61], off
	s_waitcnt lgkmcnt(8)
	s_barrier
	s_waitcnt lgkmcnt(0)
	s_setprio 1
	s_waitcnt lgkmcnt(0)
	v_mfma_f32_16x16x128_f8f6f4 v[206:209], v[6:13], v[22:29], v[206:209]
	v_mfma_f32_16x16x128_f8f6f4 v[210:213], v[14:21], v[22:29], v[210:213]
	v_mfma_f32_16x16x128_f8f6f4 v[76:79], v[6:13], v[36:43], v[76:79]
	v_mfma_f32_16x16x128_f8f6f4 v[80:83], v[14:21], v[36:43], v[80:83]
	v_mfma_f32_16x16x128_f8f6f4 v[84:87], v[6:13], v[44:51], v[84:87]
	v_mfma_f32_16x16x128_f8f6f4 v[88:91], v[14:21], v[44:51], v[88:91]
	v_mfma_f32_16x16x128_f8f6f4 v[92:95], v[6:13], v[52:59], v[92:95]
	v_mfma_f32_16x16x128_f8f6f4 v[96:99], v[14:21], v[52:59], v[96:99]
	s_setprio 0
	s_barrier
	s_mov_b32 m0, s47
	v_lshl_add_u64 v[132:133], v[2:3], 0, s[94:95]
	s_mov_b64 s[50:51], 0x10300
	ds_read_b128 v[60:63], v181
	ds_read_b128 v[64:67], v181 offset:16
	ds_read_b128 v[68:71], v181 offset:2048
	ds_read_b128 v[72:75], v181 offset:2064
	global_load_lds_dwordx4 v[132:133], off
	v_lshl_add_u64 v[132:133], v[2:3], 0, s[50:51]
	s_mov_b32 m0, s18
	s_nop 0
	global_load_lds_dwordx4 v[132:133], off
	s_barrier
	s_waitcnt lgkmcnt(0)
	s_setprio 1
	s_waitcnt lgkmcnt(0)
	v_mfma_f32_16x16x128_f8f6f4 v[100:103], v[60:67], v[22:29], v[100:103]
	v_mfma_f32_16x16x128_f8f6f4 v[104:107], v[68:75], v[22:29], v[104:107]
	v_mfma_f32_16x16x128_f8f6f4 v[108:111], v[60:67], v[36:43], v[108:111]
	v_mfma_f32_16x16x128_f8f6f4 v[112:115], v[68:75], v[36:43], v[112:115]
	v_mfma_f32_16x16x128_f8f6f4 v[116:119], v[60:67], v[44:51], v[116:119]
	v_mfma_f32_16x16x128_f8f6f4 v[120:123], v[68:75], v[44:51], v[120:123]
	v_mfma_f32_16x16x128_f8f6f4 v[124:127], v[60:67], v[52:59], v[124:127]
	v_mfma_f32_16x16x128_f8f6f4 v[136:139], v[68:75], v[52:59], v[136:139]
	s_setprio 0
	s_mov_b32 m0, s29
	v_lshl_add_u64 v[132:133], v[0:1], 0, s[94:95]
	s_mov_b64 s[50:51], 0x1fb00
	s_barrier
	ds_read_b128 v[22:25], v179 offset:16384
	ds_read_b128 v[26:29], v179 offset:16400
	ds_read_b128 v[36:39], v179 offset:18432
	ds_read_b128 v[40:43], v179 offset:18448
	ds_read_b128 v[44:47], v179 offset:20480
	ds_read_b128 v[48:51], v179 offset:20496
	ds_read_b128 v[52:55], v179 offset:22528
	ds_read_b128 v[56:59], v179 offset:22544
	global_load_lds_dwordx4 v[132:133], off
	v_lshl_add_u64 v[132:133], v[0:1], 0, s[50:51]
	s_mov_b32 m0, s33
	s_nop 0
	global_load_lds_dwordx4 v[132:133], off
	s_barrier
	s_waitcnt lgkmcnt(0)
	s_setprio 1
	s_waitcnt lgkmcnt(0)
	v_mfma_f32_16x16x128_f8f6f4 v[140:143], v[6:13], v[22:29], v[140:143]
	v_mfma_f32_16x16x128_f8f6f4 v[144:147], v[14:21], v[22:29], v[144:147]
	v_mfma_f32_16x16x128_f8f6f4 v[148:151], v[6:13], v[36:43], v[148:151]
	v_mfma_f32_16x16x128_f8f6f4 v[152:155], v[14:21], v[36:43], v[152:155]
	v_mfma_f32_16x16x128_f8f6f4 v[156:159], v[6:13], v[44:51], v[156:159]
	v_mfma_f32_16x16x128_f8f6f4 v[160:163], v[14:21], v[44:51], v[160:163]
	v_mfma_f32_16x16x128_f8f6f4 v[164:167], v[6:13], v[52:59], v[164:167]
	v_mfma_f32_16x16x128_f8f6f4 v[168:171], v[14:21], v[52:59], v[168:171]
	s_setprio 0
	s_barrier
	s_mov_b64 s[50:51], 0x20300
	s_mov_b32 m0, s19
	v_lshl_add_u64 v[6:7], v[2:3], 0, s[50:51]
	s_mov_b64 s[50:51], 0x30300
	global_load_lds_dwordx4 v[6:7], off
	v_lshl_add_u64 v[6:7], v[2:3], 0, s[50:51]
	s_mov_b32 m0, s20
	s_nop 0
	global_load_lds_dwordx4 v[6:7], off
	s_waitcnt vmcnt(6)
	s_barrier
	s_setprio 1
	v_mfma_f32_16x16x128_f8f6f4 v[172:175], v[60:67], v[22:29], v[172:175]
	v_mfma_f32_16x16x128_f8f6f4 v[182:185], v[68:75], v[22:29], v[182:185]
	v_mfma_f32_16x16x128_f8f6f4 v[186:189], v[60:67], v[36:43], v[186:189]
	v_mfma_f32_16x16x128_f8f6f4 v[30:33], v[68:75], v[36:43], v[30:33]
	v_mfma_f32_16x16x128_f8f6f4 v[190:193], v[60:67], v[44:51], v[190:193]
	v_mfma_f32_16x16x128_f8f6f4 v[194:197], v[68:75], v[44:51], v[194:197]
	v_mfma_f32_16x16x128_f8f6f4 v[198:201], v[60:67], v[52:59], v[198:201]
	v_mfma_f32_16x16x128_f8f6f4 v[202:205], v[68:75], v[52:59], v[202:205]
	s_setprio 0
	s_barrier
	ds_read_b128 v[6:9], v4
	ds_read_b128 v[10:13], v4 offset:16
	ds_read_b128 v[14:17], v4 offset:2048
	ds_read_b128 v[18:21], v4 offset:2064
	s_mov_b64 s[50:51], 0x1300
	s_mov_b32 m0, s39
	v_lshl_add_u64 v[60:61], v[0:1], 0, s[50:51]
	s_mov_b64 s[50:51], 0x20b00
	ds_read_b128 v[22:25], v179 offset:32768
	ds_read_b128 v[26:29], v179 offset:32784
	ds_read_b128 v[36:39], v179 offset:34816
	ds_read_b128 v[40:43], v179 offset:34832
	ds_read_b128 v[44:47], v179 offset:36864
	ds_read_b128 v[48:51], v179 offset:36880
	ds_read_b128 v[52:55], v179 offset:38912
	ds_read_b128 v[56:59], v179 offset:38928
	global_load_lds_dwordx4 v[60:61], off
	v_lshl_add_u64 v[60:61], v[0:1], 0, s[50:51]
	s_mov_b32 m0, s88
	s_nop 0
	global_load_lds_dwordx4 v[60:61], off
	s_waitcnt lgkmcnt(8)
	s_barrier
	s_waitcnt lgkmcnt(0)
	s_setprio 1
	s_waitcnt lgkmcnt(0)
	v_mfma_f32_16x16x128_f8f6f4 v[206:209], v[6:13], v[22:29], v[206:209]
	v_mfma_f32_16x16x128_f8f6f4 v[210:213], v[14:21], v[22:29], v[210:213]
	v_mfma_f32_16x16x128_f8f6f4 v[76:79], v[6:13], v[36:43], v[76:79]
	v_mfma_f32_16x16x128_f8f6f4 v[80:83], v[14:21], v[36:43], v[80:83]
	v_mfma_f32_16x16x128_f8f6f4 v[84:87], v[6:13], v[44:51], v[84:87]
	v_mfma_f32_16x16x128_f8f6f4 v[88:91], v[14:21], v[44:51], v[88:91]
	v_mfma_f32_16x16x128_f8f6f4 v[92:95], v[6:13], v[52:59], v[92:95]
	v_mfma_f32_16x16x128_f8f6f4 v[96:99], v[14:21], v[52:59], v[96:99]
	s_setprio 0
	s_barrier
	s_mov_b32 m0, s48
	v_lshl_add_u64 v[132:133], v[2:3], 0, s[96:97]
	s_mov_b64 s[50:51], 0x10380
	ds_read_b128 v[60:63], v34
	ds_read_b128 v[64:67], v34 offset:16
	ds_read_b128 v[68:71], v34 offset:2048
	ds_read_b128 v[72:75], v34 offset:2064
	global_load_lds_dwordx4 v[132:133], off
	v_lshl_add_u64 v[132:133], v[2:3], 0, s[50:51]
	s_mov_b32 m0, s21
	s_nop 0
	global_load_lds_dwordx4 v[132:133], off
	s_barrier
	s_waitcnt lgkmcnt(0)
	s_setprio 1
	s_waitcnt lgkmcnt(0)
	v_mfma_f32_16x16x128_f8f6f4 v[100:103], v[60:67], v[22:29], v[100:103]
	v_mfma_f32_16x16x128_f8f6f4 v[104:107], v[68:75], v[22:29], v[104:107]
	v_mfma_f32_16x16x128_f8f6f4 v[108:111], v[60:67], v[36:43], v[108:111]
	v_mfma_f32_16x16x128_f8f6f4 v[112:115], v[68:75], v[36:43], v[112:115]
	v_mfma_f32_16x16x128_f8f6f4 v[116:119], v[60:67], v[44:51], v[116:119]
	v_mfma_f32_16x16x128_f8f6f4 v[120:123], v[68:75], v[44:51], v[120:123]
	v_mfma_f32_16x16x128_f8f6f4 v[124:127], v[60:67], v[52:59], v[124:127]
	v_mfma_f32_16x16x128_f8f6f4 v[136:139], v[68:75], v[52:59], v[136:139]
	s_setprio 0
	s_mov_b32 m0, s75
	v_lshl_add_u64 v[132:133], v[0:1], 0, s[96:97]
	s_mov_b64 s[50:51], 0x1fb80
	s_barrier
	ds_read_b128 v[22:25], v179 offset:49152
	ds_read_b128 v[26:29], v179 offset:49168
	ds_read_b128 v[36:39], v179 offset:51200
	ds_read_b128 v[40:43], v179 offset:51216
	ds_read_b128 v[44:47], v179 offset:53248
	ds_read_b128 v[48:51], v179 offset:53264
	ds_read_b128 v[52:55], v179 offset:55296
	ds_read_b128 v[56:59], v179 offset:55312
	global_load_lds_dwordx4 v[132:133], off
	v_lshl_add_u64 v[132:133], v[0:1], 0, s[50:51]
	s_mov_b32 m0, s22
	s_nop 0
	global_load_lds_dwordx4 v[132:133], off
	s_barrier
	s_waitcnt lgkmcnt(0)
	s_setprio 1
	s_waitcnt lgkmcnt(0)
	v_mfma_f32_16x16x128_f8f6f4 v[140:143], v[6:13], v[22:29], v[140:143]
	v_mfma_f32_16x16x128_f8f6f4 v[144:147], v[14:21], v[22:29], v[144:147]
	v_mfma_f32_16x16x128_f8f6f4 v[148:151], v[6:13], v[36:43], v[148:151]
	v_mfma_f32_16x16x128_f8f6f4 v[152:155], v[14:21], v[36:43], v[152:155]
	v_mfma_f32_16x16x128_f8f6f4 v[156:159], v[6:13], v[44:51], v[156:159]
	v_mfma_f32_16x16x128_f8f6f4 v[160:163], v[14:21], v[44:51], v[160:163]
	v_mfma_f32_16x16x128_f8f6f4 v[164:167], v[6:13], v[52:59], v[164:167]
	v_mfma_f32_16x16x128_f8f6f4 v[168:171], v[14:21], v[52:59], v[168:171]
	s_setprio 0
	s_barrier
	s_mov_b64 s[50:51], 0x20380
	s_mov_b32 m0, s44
	v_lshl_add_u64 v[6:7], v[2:3], 0, s[50:51]
	s_mov_b64 s[50:51], 0x30380
	global_load_lds_dwordx4 v[6:7], off
	v_lshl_add_u64 v[2:3], v[2:3], 0, s[50:51]
	s_mov_b32 m0, s45
	s_nop 0
	global_load_lds_dwordx4 v[2:3], off
	s_waitcnt vmcnt(6)
	s_barrier
	s_setprio 1
	v_mfma_f32_16x16x128_f8f6f4 v[172:175], v[60:67], v[22:29], v[172:175]
	v_mfma_f32_16x16x128_f8f6f4 v[182:185], v[68:75], v[22:29], v[182:185]
	v_mfma_f32_16x16x128_f8f6f4 v[186:189], v[60:67], v[36:43], v[186:189]
	v_mfma_f32_16x16x128_f8f6f4 v[218:221], v[68:75], v[36:43], v[30:33]
	v_mfma_f32_16x16x128_f8f6f4 v[190:193], v[60:67], v[44:51], v[190:193]
	v_mfma_f32_16x16x128_f8f6f4 v[194:197], v[68:75], v[44:51], v[194:197]
	v_mfma_f32_16x16x128_f8f6f4 v[198:201], v[60:67], v[52:59], v[198:201]
	v_mfma_f32_16x16x128_f8f6f4 v[202:205], v[68:75], v[52:59], v[202:205]
	s_setprio 0
	s_barrier
	ds_read_b128 v[6:9], v180
	ds_read_b128 v[10:13], v180 offset:16
	ds_read_b128 v[14:17], v180 offset:2048
	ds_read_b128 v[18:21], v180 offset:2064
	s_mov_b64 s[50:51], 0x1380
	s_mov_b32 m0, s49
	v_lshl_add_u64 v[2:3], v[0:1], 0, s[50:51]
	s_mov_b64 s[50:51], 0x20b80
	ds_read_b128 v[22:25], v179
	ds_read_b128 v[26:29], v179 offset:16
	ds_read_b128 v[36:39], v179 offset:2048
	ds_read_b128 v[40:43], v179 offset:2064
	ds_read_b128 v[44:47], v179 offset:4096
	ds_read_b128 v[48:51], v179 offset:4112
	ds_read_b128 v[52:55], v179 offset:6144
	ds_read_b128 v[56:59], v179 offset:6160
	global_load_lds_dwordx4 v[2:3], off
	v_lshl_add_u64 v[0:1], v[0:1], 0, s[50:51]
	s_mov_b32 m0, s1
	s_nop 0
	global_load_lds_dwordx4 v[0:1], off
	s_waitcnt lgkmcnt(8)
	s_barrier
	s_waitcnt lgkmcnt(0)
	s_setprio 1
	s_waitcnt lgkmcnt(0)
	v_mfma_f32_16x16x128_f8f6f4 v[0:3], v[6:13], v[22:29], v[206:209]
	v_mfma_f32_16x16x128_f8f6f4 v[206:209], v[14:21], v[22:29], v[210:213]
	v_mfma_f32_16x16x128_f8f6f4 v[76:79], v[6:13], v[36:43], v[76:79]
	v_mfma_f32_16x16x128_f8f6f4 v[210:213], v[14:21], v[36:43], v[80:83]
	v_mfma_f32_16x16x128_f8f6f4 v[222:225], v[6:13], v[44:51], v[84:87]
	v_mfma_f32_16x16x128_f8f6f4 v[226:229], v[14:21], v[44:51], v[88:91]
	v_mfma_f32_16x16x128_f8f6f4 v[230:233], v[6:13], v[52:59], v[92:95]
	v_mfma_f32_16x16x128_f8f6f4 v[96:99], v[14:21], v[52:59], v[96:99]
	s_setprio 0
	s_barrier
	s_mov_b32 m0, s47
	v_lshl_add_u64 v[32:33], s[2:3], 0, v[128:129]
	s_mov_b64 s[2:3], 0x10000
	ds_read_b128 v[60:63], v181
	ds_read_b128 v[64:67], v181 offset:16
	ds_read_b128 v[68:71], v181 offset:2048
	ds_read_b128 v[72:75], v181 offset:2064
	global_load_lds_dwordx4 v[32:33], off
	v_lshl_add_u64 v[30:31], v[32:33], 0, s[2:3]
	s_mov_b32 m0, s18
	s_nop 0
	global_load_lds_dwordx4 v[30:31], off
	s_barrier
	s_waitcnt lgkmcnt(0)
	s_setprio 1
	s_waitcnt lgkmcnt(0)
	v_mfma_f32_16x16x128_f8f6f4 v[234:237], v[60:67], v[22:29], v[100:103]
	v_mfma_f32_16x16x128_f8f6f4 v[238:241], v[68:75], v[22:29], v[104:107]
	v_mfma_f32_16x16x128_f8f6f4 v[242:245], v[60:67], v[36:43], v[108:111]
	v_mfma_f32_16x16x128_f8f6f4 v[112:115], v[68:75], v[36:43], v[112:115]
	v_mfma_f32_16x16x128_f8f6f4 v[116:119], v[60:67], v[44:51], v[116:119]
	v_mfma_f32_16x16x128_f8f6f4 v[120:123], v[68:75], v[44:51], v[120:123]
	v_mfma_f32_16x16x128_f8f6f4 v[124:127], v[60:67], v[52:59], v[124:127]
	v_mfma_f32_16x16x128_f8f6f4 v[136:139], v[68:75], v[52:59], v[136:139]
	s_setprio 0
	s_mov_b32 m0, s29
	v_lshl_add_u64 v[176:177], s[14:15], 0, v[130:131]
	s_mov_b64 s[2:3], 0x1f800
	s_barrier
	ds_read_b128 v[22:25], v179 offset:16384
	ds_read_b128 v[26:29], v179 offset:16400
	ds_read_b128 v[36:39], v179 offset:18432
	ds_read_b128 v[40:43], v179 offset:18448
	ds_read_b128 v[44:47], v179 offset:20480
	ds_read_b128 v[48:51], v179 offset:20496
	ds_read_b128 v[52:55], v179 offset:22528
	ds_read_b128 v[56:59], v179 offset:22544
	global_load_lds_dwordx4 v[176:177], off
	v_lshl_add_u64 v[30:31], v[176:177], 0, s[2:3]
	s_mov_b32 m0, s33
	s_nop 0
	global_load_lds_dwordx4 v[30:31], off
	s_barrier
	s_waitcnt lgkmcnt(0)
	s_setprio 1
	s_waitcnt lgkmcnt(0)
	v_mfma_f32_16x16x128_f8f6f4 v[246:249], v[6:13], v[22:29], v[140:143]
	v_mfma_f32_16x16x128_f8f6f4 v[214:217], v[14:21], v[22:29], v[144:147]
	v_mfma_f32_16x16x128_f8f6f4 v[132:135], v[6:13], v[36:43], v[148:151]
	v_mfma_f32_16x16x128_f8f6f4 v[152:155], v[14:21], v[36:43], v[152:155]
	v_mfma_f32_16x16x128_f8f6f4 v[156:159], v[6:13], v[44:51], v[156:159]
	v_mfma_f32_16x16x128_f8f6f4 v[160:163], v[14:21], v[44:51], v[160:163]
	v_mfma_f32_16x16x128_f8f6f4 v[164:167], v[6:13], v[52:59], v[164:167]
	v_mfma_f32_16x16x128_f8f6f4 v[168:171], v[14:21], v[52:59], v[168:171]
	s_setprio 0
	s_barrier
	s_mov_b64 s[2:3], 0x20000
	s_mov_b32 m0, s19
	v_lshl_add_u64 v[6:7], v[32:33], 0, s[2:3]
	s_mov_b64 s[2:3], 0x30000
	global_load_lds_dwordx4 v[6:7], off
	v_lshl_add_u64 v[6:7], v[32:33], 0, s[2:3]
	s_mov_b32 m0, s20
	s_nop 0
	global_load_lds_dwordx4 v[6:7], off
	s_waitcnt vmcnt(6)
	s_barrier
	s_setprio 1
	v_mfma_f32_16x16x128_f8f6f4 v[172:175], v[60:67], v[22:29], v[172:175]
	v_mfma_f32_16x16x128_f8f6f4 v[182:185], v[68:75], v[22:29], v[182:185]
	v_mfma_f32_16x16x128_f8f6f4 v[186:189], v[60:67], v[36:43], v[186:189]
	v_mfma_f32_16x16x128_f8f6f4 v[218:221], v[68:75], v[36:43], v[218:221]
	v_mfma_f32_16x16x128_f8f6f4 v[190:193], v[60:67], v[44:51], v[190:193]
	v_mfma_f32_16x16x128_f8f6f4 v[194:197], v[68:75], v[44:51], v[194:197]
	v_mfma_f32_16x16x128_f8f6f4 v[198:201], v[60:67], v[52:59], v[198:201]
	v_mfma_f32_16x16x128_f8f6f4 v[202:205], v[68:75], v[52:59], v[202:205]
	s_setprio 0
	s_barrier
	ds_read_b128 v[80:83], v4
	ds_read_b128 v[84:87], v4 offset:16
	ds_read_b128 v[88:91], v4 offset:2048
	ds_read_b128 v[92:95], v4 offset:2064
	s_mov_b32 m0, s39
	v_lshl_add_u64 v[4:5], v[176:177], 0, s[12:13]
	ds_read_b128 v[36:39], v179 offset:32768
	ds_read_b128 v[40:43], v179 offset:32784
	ds_read_b128 v[44:47], v179 offset:34816
	ds_read_b128 v[48:51], v179 offset:34832
	ds_read_b128 v[60:63], v179 offset:36864
	ds_read_b128 v[64:67], v179 offset:36880
	ds_read_b128 v[68:71], v179 offset:38912
	ds_read_b128 v[72:75], v179 offset:38928
	global_load_lds_dwordx4 v[4:5], off
	v_lshl_add_u64 v[4:5], v[176:177], 0, s[68:69]
	s_mov_b32 m0, s88
	s_nop 0
	global_load_lds_dwordx4 v[4:5], off
	s_waitcnt lgkmcnt(8)
	s_barrier
	s_waitcnt lgkmcnt(0)
	s_setprio 1
	s_waitcnt lgkmcnt(0)
	v_mfma_f32_16x16x128_f8f6f4 v[16:19], v[80:87], v[36:43], v[0:3]
	v_mfma_f32_16x16x128_f8f6f4 v[0:3], v[88:95], v[36:43], v[206:209]
	v_mfma_f32_16x16x128_f8f6f4 v[20:23], v[80:87], v[44:51], v[76:79]
	v_mfma_f32_16x16x128_f8f6f4 v[4:7], v[88:95], v[44:51], v[210:213]
	v_mfma_f32_16x16x128_f8f6f4 v[24:27], v[80:87], v[60:67], v[222:225]
	v_mfma_f32_16x16x128_f8f6f4 v[8:11], v[88:95], v[60:67], v[226:229]
	v_mfma_f32_16x16x128_f8f6f4 v[28:31], v[80:87], v[68:75], v[230:233]
	v_mfma_f32_16x16x128_f8f6f4 v[12:15], v[88:95], v[68:75], v[96:99]
	s_setprio 0
	s_barrier
	s_mov_b32 m0, s48
	s_nop 3
	ds_read_b128 v[96:99], v34
	ds_read_b128 v[100:103], v34 offset:16
	ds_read_b128 v[104:107], v34 offset:2048
	ds_read_b128 v[108:111], v34 offset:2064
	v_lshl_add_u64 v[34:35], v[32:33], 0, s[72:73]
	global_load_lds_dwordx4 v[34:35], off
	v_lshl_add_u64 v[34:35], v[32:33], 0, s[76:77]
	s_mov_b32 m0, s21
	s_nop 0
	global_load_lds_dwordx4 v[34:35], off
	s_barrier
	s_waitcnt lgkmcnt(0)
	s_setprio 1
	s_waitcnt lgkmcnt(0)
	v_mfma_f32_16x16x128_f8f6f4 v[206:209], v[96:103], v[36:43], v[234:237]
	v_mfma_f32_16x16x128_f8f6f4 v[56:59], v[104:111], v[36:43], v[238:241]
	v_mfma_f32_16x16x128_f8f6f4 v[34:37], v[96:103], v[44:51], v[242:245]
	v_mfma_f32_16x16x128_f8f6f4 v[52:55], v[104:111], v[44:51], v[112:115]
	v_mfma_f32_16x16x128_f8f6f4 v[210:213], v[96:103], v[60:67], v[116:119]
	v_mfma_f32_16x16x128_f8f6f4 v[44:47], v[104:111], v[60:67], v[120:123]
	v_mfma_f32_16x16x128_f8f6f4 v[222:225], v[96:103], v[68:75], v[124:127]
	v_mfma_f32_16x16x128_f8f6f4 v[40:43], v[104:111], v[68:75], v[136:139]
	s_setprio 0
	s_mov_b32 m0, s75
	v_lshl_add_u64 v[38:39], v[176:177], 0, s[72:73]
	s_barrier
	ds_read_b128 v[112:115], v179 offset:49152
	ds_read_b128 v[116:119], v179 offset:49168
	ds_read_b128 v[120:123], v179 offset:51200
	ds_read_b128 v[124:127], v179 offset:51216
	ds_read_b128 v[136:139], v179 offset:53248
	ds_read_b128 v[140:143], v179 offset:53264
	ds_read_b128 v[144:147], v179 offset:55296
	ds_read_b128 v[148:151], v179 offset:55312
	global_load_lds_dwordx4 v[38:39], off
	v_lshl_add_u64 v[38:39], v[176:177], 0, s[78:79]
	s_mov_b32 m0, s22
	s_nop 0
	global_load_lds_dwordx4 v[38:39], off
	s_barrier
	s_waitcnt lgkmcnt(0)
	s_setprio 1
	s_waitcnt lgkmcnt(0)
	v_mfma_f32_16x16x128_f8f6f4 v[226:229], v[80:87], v[112:119], v[246:249]
	v_mfma_f32_16x16x128_f8f6f4 v[64:67], v[88:95], v[112:119], v[214:217]
	v_mfma_f32_16x16x128_f8f6f4 v[132:135], v[80:87], v[120:127], v[132:135]
	v_mfma_f32_16x16x128_f8f6f4 v[76:79], v[88:95], v[120:127], v[152:155]
	v_mfma_f32_16x16x128_f8f6f4 v[152:155], v[80:87], v[136:143], v[156:159]
	v_mfma_f32_16x16x128_f8f6f4 v[68:71], v[88:95], v[136:143], v[160:163]
	v_mfma_f32_16x16x128_f8f6f4 v[158:161], v[80:87], v[144:151], v[164:167]
	v_mfma_f32_16x16x128_f8f6f4 v[72:75], v[88:95], v[144:151], v[168:171]
	s_setprio 0
	s_barrier
	s_mov_b32 m0, s44
	v_lshl_add_u64 v[38:39], v[32:33], 0, s[80:81]
	global_load_lds_dwordx4 v[38:39], off
	v_lshl_add_u64 v[32:33], v[32:33], 0, s[82:83]
	s_mov_b32 m0, s45
	s_nop 0
	global_load_lds_dwordx4 v[32:33], off
	s_waitcnt vmcnt(6)
	s_barrier
	s_setprio 1
	v_mfma_f32_16x16x128_f8f6f4 v[164:167], v[96:103], v[112:119], v[172:175]
	v_mfma_f32_16x16x128_f8f6f4 v[92:95], v[104:111], v[112:119], v[182:185]
	v_mfma_f32_16x16x128_f8f6f4 v[174:177], v[96:103], v[120:127], v[186:189]
	v_mfma_f32_16x16x128_f8f6f4 v[88:91], v[104:111], v[120:127], v[218:221]
	v_mfma_f32_16x16x128_f8f6f4 v[184:187], v[96:103], v[136:143], v[190:193]
	v_mfma_f32_16x16x128_f8f6f4 v[84:87], v[104:111], v[136:143], v[194:197]
	v_mfma_f32_16x16x128_f8f6f4 v[188:191], v[96:103], v[144:151], v[198:201]
	v_mfma_f32_16x16x128_f8f6f4 v[80:83], v[104:111], v[144:151], v[202:205]
	s_setprio 0
	s_mov_b32 s1, 0
	s_barrier
	v_mul_f32_e64 v146, v134, s38
	v_mul_f32_e64 v147, v135, s38
	v_mbcnt_lo_u32_b32 v32, -1, s1
	v_mbcnt_hi_u32_b32 v32, -1, v32
	s_lshl_b32 s1, s46, 7
	s_or_b32 s1, s1, s74
	v_ashrrev_i32_e32 v63, 4, v32
	v_lshl_add_u32 v136, v63, 3, s1
	v_ashrrev_i32_e32 v137, 31, v136
	v_lshlrev_b64 v[38:39], 2, v[136:137]
	v_and_b32_e32 v62, 15, v32
	v_lshl_add_u64 v[32:33], s[62:63], 0, v[38:39]
	v_lshl_add_u64 v[48:49], s[60:61], 0, v[38:39]
	v_lshl_add_u64 v[50:51], s[34:35], 0, v[38:39]
	global_load_dwordx4 v[96:99], v[48:49], off
	global_load_dwordx4 v[100:103], v[50:51], off
	v_lshl_add_u64 v[50:51], s[36:37], 0, v[38:39]
	v_add_co_u32_e32 v60, vcc, s89, v32
	global_load_dwordx4 v[104:107], v[50:51], off
	global_load_dwordx4 v[120:123], v[32:33], off
	v_lshl_add_u64 v[50:51], s[58:59], 0, v[38:39]
	v_addc_co_u32_e32 v61, vcc, 0, v33, vcc
	global_load_dwordx4 v[108:111], v[50:51], off
	v_lshl_add_u64 v[50:51], s[64:65], 0, v[38:39]
	global_load_dwordx4 v[124:127], v[60:61], off offset:2560
	global_load_dwordx4 v[112:115], v[50:51], off
	v_lshl_add_u64 v[38:39], s[66:67], 0, v[38:39]
	global_load_dwordx4 v[116:119], v[38:39], off
	s_mul_hi_i32 s1, s9, 0x3e0f83e1
	s_lshr_b32 s2, s1, 31
	s_ashr_i32 s1, s1, 3
	s_add_i32 s1, s1, s2
	s_mul_i32 s2, s1, 0xffffffdf
	s_add_i32 s2, s2, s9
	s_mulk_i32 s2, 0xfc
	s_add_i32 s2, s2, s23
	v_lshlrev_b32_e32 v138, 3, v62
	v_add_u32_e32 v183, s2, v138
	v_lshl_or_b32 v38, v63, 7, v138
	v_cmp_gt_i32_e64 s[44:45], 1, v183
	v_add_u32_e32 v137, 0xa800000, v38
	v_pk_mul_f32 v[38:39], v[208:209], s[38:39] op_sel_hi:[1,0]
	v_pk_mul_f32 v[134:135], v[18:19], s[38:39] op_sel_hi:[1,0]
	v_pk_mul_f32 v[138:139], v[176:177], s[38:39] op_sel_hi:[1,0]
	v_pk_mul_f32 v[144:145], v[184:185], s[38:39] op_sel_hi:[1,0]
	v_pk_mul_f32 v[176:177], v[28:29], s[38:39] op_sel_hi:[1,0]
	v_cndmask_b32_e64 v29, v39, 0, s[44:45]
	v_cndmask_b32_e64 v28, v38, 0, s[44:45]
	v_cndmask_b32_e64 v39, v135, 0, s[44:45]
	v_cndmask_b32_e64 v38, v134, 0, s[44:45]
	v_pk_mul_f32 v[142:143], v[186:187], s[38:39] op_sel_hi:[1,0]
	v_pk_mul_f32 v[150:151], v[160:161], s[38:39] op_sel_hi:[1,0]
	v_pk_mul_f32 v[160:161], v[152:153], s[38:39] op_sel_hi:[1,0]
	v_pk_mul_f32 v[152:153], v[188:189], s[38:39] op_sel_hi:[1,0]
	v_mov_b32_dpp v134, v144 row_shr:1 row_mask:0xf bank_mask:0xf bound_ctrl:1
	v_mov_b32_dpp v135, v145 row_shr:1 row_mask:0xf bank_mask:0xf bound_ctrl:1
	v_pk_mul_f32 v[50:51], v[206:207], s[38:39] op_sel_hi:[1,0]
	v_mov_b32_dpp v186, v152 row_shr:1 row_mask:0xf bank_mask:0xf bound_ctrl:1
	v_mov_b32_dpp v187, v153 row_shr:1 row_mask:0xf bank_mask:0xf bound_ctrl:1
	v_pk_mul_f32 v[140:141], v[174:175], s[38:39] op_sel_hi:[1,0]
	v_pk_mul_f32 v[174:175], v[30:31], s[38:39] op_sel_hi:[1,0]
	v_cndmask_b32_e64 v31, v51, 0, s[44:45]
	v_cndmask_b32_e64 v30, v50, 0, s[44:45]
	v_cmp_ne_u32_e32 vcc, 0, v62
	v_pk_mul_f32 v[62:63], v[36:37], s[38:39] op_sel_hi:[1,0]
	v_pk_mul_f32 v[192:193], v[34:35], s[38:39] op_sel_hi:[1,0]
	v_pk_mul_f32 v[148:149], v[154:155], s[38:39] op_sel_hi:[1,0]
	v_pk_mul_f32 v[156:157], v[132:133], s[38:39] op_sel_hi:[1,0]
	v_pk_mul_f32 v[132:133], v[16:17], s[38:39] op_sel_hi:[1,0]
	v_pk_mul_f32 v[154:155], v[190:191], s[38:39] op_sel_hi:[1,0]
	v_cndmask_b32_e64 v17, v63, 0, s[44:45]
	v_cndmask_b32_e64 v16, v62, 0, s[44:45]
	v_pk_mul_f32 v[18:19], v[24:25], s[38:39] op_sel_hi:[1,0]
	v_pk_mul_f32 v[158:159], v[158:159], s[38:39] op_sel_hi:[1,0]
	v_pk_mul_f32 v[24:25], v[20:21], s[38:39] op_sel_hi:[1,0]
	v_cndmask_b32_e64 v21, v193, 0, s[44:45]
	v_cndmask_b32_e64 v20, v192, 0, s[44:45]
	v_cndmask_b32_e64 v51, v133, 0, s[44:45]
	v_cndmask_b32_e64 v50, v132, 0, s[44:45]
	v_mov_b32_dpp v62, v160 row_shr:1 row_mask:0xf bank_mask:0xf bound_ctrl:1
	v_mov_b32_dpp v63, v161 row_shr:1 row_mask:0xf bank_mask:0xf bound_ctrl:1
	v_mov_b32_dpp v190, v142 row_shr:1 row_mask:0xf bank_mask:0xf bound_ctrl:1
	v_mov_b32_dpp v191, v143 row_shr:1 row_mask:0xf bank_mask:0xf bound_ctrl:1
	v_mov_b32_dpp v132, v158 row_shr:1 row_mask:0xf bank_mask:0xf bound_ctrl:1
	v_mov_b32_dpp v133, v159 row_shr:1 row_mask:0xf bank_mask:0xf bound_ctrl:1
	v_mov_b32_dpp v192, v154 row_shr:1 row_mask:0xf bank_mask:0xf bound_ctrl:1
	v_mov_b32_dpp v193, v155 row_shr:1 row_mask:0xf bank_mask:0xf bound_ctrl:1
	s_waitcnt vmcnt(0)
	v_pk_fma_f32 v[62:63], v[96:97], v[62:63], v[120:121]
	v_pk_fma_f32 v[62:63], v[100:101], v[132:133], v[62:63]
	v_pk_fma_f32 v[62:63], v[104:105], v[50:51], v[62:63]
	v_pk_fma_f32 v[134:135], v[108:109], v[134:135], v[124:125]
	v_pk_fma_f32 v[190:191], v[110:111], v[190:191], v[126:127]
	v_pk_fma_f32 v[134:135], v[112:113], v[186:187], v[134:135]
	v_pk_fma_f32 v[190:191], v[114:115], v[192:193], v[190:191]
	v_pk_fma_f32 v[134:135], v[30:31], v[116:117], v[134:135]
	v_pk_fma_f32 v[190:191], v[28:29], v[118:119], v[190:191]
	v_mul_f32_e32 v194, 0xbfb8aa3b, v134
	v_mul_f32_e32 v195, 0xbfb8aa3b, v135
	v_exp_f32_e32 v194, v194
	v_exp_f32_e32 v195, v195
	v_mov_b32_dpp v184, v148 row_shr:1 row_mask:0xf bank_mask:0xf bound_ctrl:1
	v_add_f32_e32 v194, 1.0, v194
	v_add_f32_e32 v195, 1.0, v195
	v_rcp_f32_e32 v194, v194
	v_rcp_f32_e32 v195, v195
	v_mov_b32_dpp v185, v149 row_shr:1 row_mask:0xf bank_mask:0xf bound_ctrl:1
	v_mov_b32_dpp v188, v150 row_shr:1 row_mask:0xf bank_mask:0xf bound_ctrl:1
	v_pk_mul_f32 v[134:135], v[134:135], v[194:195]
	v_mov_b32_dpp v189, v151 row_shr:1 row_mask:0xf bank_mask:0xf bound_ctrl:1
	v_pk_mul_f32 v[62:63], v[62:63], v[134:135]
	v_mul_f32_e32 v134, 0xbfb8aa3b, v190
	v_mul_f32_e32 v135, 0xbfb8aa3b, v191
	v_exp_f32_e32 v134, v134
	v_exp_f32_e32 v135, v135
	v_pk_fma_f32 v[184:185], v[98:99], v[184:185], v[122:123]
	s_lshl_b32 s1, s1, 13
	v_add_f32_e32 v134, 1.0, v134
	v_add_f32_e32 v135, 1.0, v135
	v_rcp_f32_e32 v134, v134
	v_rcp_f32_e32 v135, v135
	v_add_u32_e32 v182, -2, v183
	v_pk_fma_f32 v[184:185], v[102:103], v[188:189], v[184:185]
	v_add_u32_e32 v196, s1, v182
	v_pk_fma_f32 v[184:185], v[106:107], v[38:39], v[184:185]
	v_pk_mul_f32 v[134:135], v[190:191], v[134:135]
	v_cmp_gt_u32_e64 s[46:47], s89, v182
	v_pk_mul_f32 v[134:135], v[184:185], v[134:135]
	v_mul_lo_u32 v184, v196, s6
	v_pk_fma_f32 v[186:187], v[108:109], v[186:187], v[124:125]
	s_and_b64 s[46:47], vcc, s[46:47]
	v_add_lshl_u32 v182, v184, v136, 1
	v_pk_fma_f32 v[186:187], v[30:31], v[112:113], v[186:187]
	v_cndmask_b32_e64 v185, v137, v182, s[46:47]
	v_cvt_pk_bf16_f32 v62, v62, v63
	v_cvt_pk_bf16_f32 v63, v134, v135
	v_pk_fma_f32 v[186:187], v[20:21], v[116:117], v[186:187]
	global_store_dwordx2 v185, v[62:63], s[70:71]
	v_mul_f32_e32 v185, 0xbfb8aa3b, v186
	v_exp_f32_e32 v185, v185
	v_pk_fma_f32 v[62:63], v[98:99], v[188:189], v[122:123]
	v_pk_fma_f32 v[134:135], v[110:111], v[192:193], v[126:127]
	v_pk_fma_f32 v[132:133], v[96:97], v[132:133], v[120:121]
	v_add_f32_e32 v185, 1.0, v185
	v_rcp_f32_e32 v188, v185
	v_mul_f32_e32 v185, 0xbfb8aa3b, v187
	v_exp_f32_e32 v185, v185
	v_pk_fma_f32 v[134:135], v[28:29], v[114:115], v[134:135]
	v_cndmask_b32_e64 v25, v25, 0, s[44:45]
	v_pk_fma_f32 v[134:135], v[16:17], v[118:119], v[134:135]
	v_add_f32_e32 v185, 1.0, v185
	v_rcp_f32_e32 v189, v185
	v_mul_f32_e32 v185, 0xbfb8aa3b, v134
	v_exp_f32_e32 v185, v185
	v_cndmask_b32_e64 v24, v24, 0, s[44:45]
	v_pk_fma_f32 v[132:133], v[100:101], v[50:51], v[132:133]
	v_pk_mul_f32 v[186:187], v[186:187], v[188:189]
	v_pk_fma_f32 v[132:133], v[104:105], v[24:25], v[132:133]
	v_add_f32_e32 v185, 1.0, v185
	v_pk_mul_f32 v[132:133], v[132:133], v[186:187]
	v_rcp_f32_e32 v186, v185
	v_mul_f32_e32 v185, 0xbfb8aa3b, v135
	v_exp_f32_e32 v185, v185
	v_pk_mul_f32 v[22:23], v[22:23], s[38:39] op_sel_hi:[1,0]
	v_pk_fma_f32 v[62:63], v[102:103], v[38:39], v[62:63]
	v_cndmask_b32_e64 v23, v23, 0, s[44:45]
	v_add_f32_e32 v185, 1.0, v185
	v_rcp_f32_e32 v187, v185
	v_cndmask_b32_e64 v22, v22, 0, s[44:45]
	v_pk_fma_f32 v[30:31], v[108:109], v[30:31], v[124:125]
	v_pk_mul_f32 v[36:37], v[210:211], s[38:39] op_sel_hi:[1,0]
	v_pk_fma_f32 v[62:63], v[106:107], v[22:23], v[62:63]
	v_pk_mul_f32 v[134:135], v[134:135], v[186:187]
	v_pk_fma_f32 v[30:31], v[20:21], v[112:113], v[30:31]
	v_pk_mul_f32 v[62:63], v[62:63], v[134:135]
	v_pk_fma_f32 v[30:31], v[36:37], v[116:117], v[30:31]
	v_cvt_pk_bf16_f32 v132, v132, v133
	v_cvt_pk_bf16_f32 v133, v62, v63
	v_mul_f32_e32 v62, 0xbfb8aa3b, v30
	v_mul_f32_e32 v63, 0xbfb8aa3b, v31
	v_exp_f32_e32 v62, v62
	v_exp_f32_e32 v63, v63
	v_pk_fma_f32 v[50:51], v[96:97], v[50:51], v[120:121]
	v_pk_fma_f32 v[28:29], v[110:111], v[28:29], v[126:127]
	v_add_f32_e32 v62, 1.0, v62
	v_add_f32_e32 v63, 1.0, v63
	v_rcp_f32_e32 v62, v62
	v_rcp_f32_e32 v63, v63
	v_pk_mul_f32 v[34:35], v[212:213], s[38:39] op_sel_hi:[1,0]
	v_pk_fma_f32 v[50:51], v[100:101], v[24:25], v[50:51]
	v_pk_fma_f32 v[28:29], v[16:17], v[114:115], v[28:29]
	v_pk_fma_f32 v[50:51], v[104:105], v[18:19], v[50:51]
	v_pk_fma_f32 v[28:29], v[34:35], v[118:119], v[28:29]
	v_pk_mul_f32 v[30:31], v[30:31], v[62:63]
	v_pk_fma_f32 v[38:39], v[98:99], v[38:39], v[122:123]
	v_pk_mul_f32 v[30:31], v[50:51], v[30:31]
	v_mul_f32_e32 v50, 0xbfb8aa3b, v28
	v_mul_f32_e32 v51, 0xbfb8aa3b, v29
	v_exp_f32_e32 v50, v50
	v_exp_f32_e32 v51, v51
	v_pk_mul_f32 v[26:27], v[26:27], s[38:39] op_sel_hi:[1,0]
	v_pk_fma_f32 v[38:39], v[102:103], v[22:23], v[38:39]
	v_add_f32_e32 v50, 1.0, v50
	v_add_f32_e32 v51, 1.0, v51
	v_rcp_f32_e32 v50, v50
	v_rcp_f32_e32 v51, v51
	v_pk_fma_f32 v[20:21], v[108:109], v[20:21], v[124:125]
	v_pk_mul_f32 v[172:173], v[222:223], s[38:39] op_sel_hi:[1,0]
	v_pk_fma_f32 v[38:39], v[106:107], v[26:27], v[38:39]
	v_pk_mul_f32 v[28:29], v[28:29], v[50:51]
	v_pk_fma_f32 v[20:21], v[36:37], v[112:113], v[20:21]
	v_pk_mul_f32 v[28:29], v[38:39], v[28:29]
	v_pk_fma_f32 v[20:21], v[172:173], v[116:117], v[20:21]
	v_cvt_pk_bf16_f32 v30, v30, v31
	v_cvt_pk_bf16_f32 v31, v28, v29
	v_mul_f32_e32 v28, 0xbfb8aa3b, v20
	v_mul_f32_e32 v29, 0xbfb8aa3b, v21
	v_exp_f32_e32 v28, v28
	v_exp_f32_e32 v29, v29
	v_pk_fma_f32 v[24:25], v[96:97], v[24:25], v[120:121]
	v_pk_fma_f32 v[16:17], v[110:111], v[16:17], v[126:127]
	v_add_f32_e32 v28, 1.0, v28
	v_add_f32_e32 v29, 1.0, v29
	v_rcp_f32_e32 v28, v28
	v_rcp_f32_e32 v29, v29
	v_pk_mul_f32 v[170:171], v[224:225], s[38:39] op_sel_hi:[1,0]
	v_pk_fma_f32 v[24:25], v[100:101], v[18:19], v[24:25]
	v_pk_fma_f32 v[16:17], v[34:35], v[114:115], v[16:17]
	v_pk_fma_f32 v[24:25], v[104:105], v[176:177], v[24:25]
	v_pk_fma_f32 v[16:17], v[170:171], v[118:119], v[16:17]
	v_pk_mul_f32 v[20:21], v[20:21], v[28:29]
	v_pk_fma_f32 v[22:23], v[98:99], v[22:23], v[122:123]
	v_pk_mul_f32 v[20:21], v[24:25], v[20:21]
	v_mul_f32_e32 v24, 0xbfb8aa3b, v16
	v_mul_f32_e32 v25, 0xbfb8aa3b, v17
	v_exp_f32_e32 v24, v24
	v_exp_f32_e32 v25, v25
	v_add_u32_e32 v134, -1, v183
	v_add_u32_e32 v38, s1, v183
	v_add_f32_e32 v24, 1.0, v24
	v_add_f32_e32 v25, 1.0, v25
	v_rcp_f32_e32 v24, v24
	v_rcp_f32_e32 v25, v25
	v_pk_fma_f32 v[22:23], v[102:103], v[26:27], v[22:23]
	v_cmp_gt_u32_e64 s[48:49], s89, v134
	v_mul_lo_u32 v185, v38, s6
	v_pk_fma_f32 v[22:23], v[106:107], v[174:175], v[22:23]
	v_pk_mul_f32 v[16:17], v[16:17], v[24:25]
	s_and_b64 s[48:49], vcc, s[48:49]
	v_add_u32_e32 v134, 0x1500, v182
	v_cmp_gt_u32_e32 vcc, s89, v183
	v_add_lshl_u32 v38, v185, v136, 1
	v_pk_mul_f32 v[16:17], v[22:23], v[16:17]
	v_add_u32_e32 v22, 0x3f00, v182
	v_cndmask_b32_e64 v134, v137, v134, s[48:49]
	v_cndmask_b32_e32 v38, v137, v38, vcc
	v_cndmask_b32_e32 v22, v137, v22, vcc
	v_cvt_pk_bf16_f32 v20, v20, v21
	v_cvt_pk_bf16_f32 v21, v16, v17
	global_store_dwordx2 v134, v[132:133], s[70:71]
	global_store_dwordx2 v38, v[30:31], s[70:71]
	global_store_dwordx2 v22, v[20:21], s[70:71]
	v_pk_fma_f32 v[22:23], v[36:37], v[108:109], v[124:125]
	v_pk_mul_f32 v[164:165], v[164:165], s[38:39] op_sel_hi:[1,0]
	v_pk_fma_f32 v[22:23], v[172:173], v[112:113], v[22:23]
	v_pk_fma_f32 v[18:19], v[96:97], v[18:19], v[120:121]
	v_pk_fma_f32 v[22:23], v[164:165], v[116:117], v[22:23]
	v_pk_fma_f32 v[20:21], v[34:35], v[110:111], v[126:127]
	v_mul_f32_e32 v24, 0xbfb8aa3b, v22
	v_mul_f32_e32 v25, 0xbfb8aa3b, v23
	v_exp_f32_e32 v24, v24
	v_exp_f32_e32 v25, v25
	v_pk_mul_f32 v[162:163], v[166:167], s[38:39] op_sel_hi:[1,0]
	v_pk_mul_f32 v[168:169], v[226:227], s[38:39] op_sel_hi:[1,0]
	v_add_f32_e32 v24, 1.0, v24
	v_add_f32_e32 v25, 1.0, v25
	v_rcp_f32_e32 v24, v24
	v_rcp_f32_e32 v25, v25
	v_pk_fma_f32 v[18:19], v[100:101], v[176:177], v[18:19]
	v_pk_fma_f32 v[20:21], v[170:171], v[114:115], v[20:21]
	v_pk_fma_f32 v[18:19], v[104:105], v[168:169], v[18:19]
	v_pk_fma_f32 v[20:21], v[162:163], v[118:119], v[20:21]
	v_pk_mul_f32 v[22:23], v[22:23], v[24:25]
	v_pk_fma_f32 v[16:17], v[98:99], v[26:27], v[122:123]
	v_pk_mul_f32 v[18:19], v[18:19], v[22:23]
	v_mul_f32_e32 v22, 0xbfb8aa3b, v20
	v_mul_f32_e32 v23, 0xbfb8aa3b, v21
	v_exp_f32_e32 v22, v22
	v_exp_f32_e32 v23, v23
	v_pk_mul_f32 v[166:167], v[228:229], s[38:39] op_sel_hi:[1,0]
	v_pk_fma_f32 v[16:17], v[102:103], v[174:175], v[16:17]
	v_add_f32_e32 v22, 1.0, v22
	v_add_f32_e32 v23, 1.0, v23
	v_rcp_f32_e32 v22, v22
	v_rcp_f32_e32 v23, v23
	v_pk_fma_f32 v[16:17], v[106:107], v[166:167], v[16:17]
	v_cvt_pk_bf16_f32 v18, v18, v19
	s_movk_i32 s1, 0x5000
	v_pk_mul_f32 v[20:21], v[20:21], v[22:23]
	v_pk_fma_f32 v[172:173], v[172:173], v[108:109], v[124:125]
	v_pk_mul_f32 v[16:17], v[16:17], v[20:21]
	v_add_u32_e32 v20, 2, v183
	v_cmp_gt_u32_e64 s[50:51], s89, v20
	v_add_u32_e32 v20, 0x5400, v182
	v_cvt_pk_bf16_f32 v19, v16, v17
	v_cndmask_b32_e64 v20, v137, v20, s[50:51]
	global_store_dwordx2 v20, v[18:19], s[70:71]
	v_add_co_u32_e64 v20, s[52:53], s1, v48
	s_mov_b32 s1, 0xa000
	s_nop 0
	v_addc_co_u32_e64 v21, s[52:53], 0, v49, s[52:53]
	v_add_co_u32_e64 v24, s[52:53], s1, v48
	global_load_dwordx4 v[16:19], v[48:49], off offset:16
	s_nop 0
	v_addc_co_u32_e64 v25, s[52:53], 0, v49, s[52:53]
	global_load_dwordx4 v[20:23], v[20:21], off offset:1040
	s_nop 0
	global_load_dwordx4 v[28:31], v[24:25], off offset:2064
	s_nop 0
	global_load_dwordx4 v[32:35], v[32:33], off offset:16
	v_add_co_u32_e64 v24, s[52:53], s89, v48
	s_movk_i32 s1, 0x7000
	s_nop 0
	v_addc_co_u32_e64 v25, s[52:53], 0, v49, s[52:53]
	v_add_co_u32_e64 v36, s[52:53], s1, v48
	s_mov_b32 s1, 0xd000
	s_nop 0
	v_addc_co_u32_e64 v37, s[52:53], 0, v49, s[52:53]
	v_add_co_u32_e64 v48, s[52:53], s1, v48
	global_load_dwordx4 v[24:27], v[24:25], off offset:2576
	s_nop 0
	v_addc_co_u32_e64 v49, s[52:53], 0, v49, s[52:53]
	global_load_dwordx4 v[36:39], v[36:37], off offset:3600
	s_nop 0
	global_load_dwordx4 v[48:51], v[48:49], off offset:528
	s_nop 0
	global_load_dwordx4 v[60:63], v[60:61], off offset:2576
	v_pk_fma_f32 v[172:173], v[164:165], v[112:113], v[172:173]
	v_pk_fma_f32 v[132:133], v[98:99], v[174:175], v[122:123]
	v_pk_fma_f32 v[172:173], v[140:141], v[116:117], v[172:173]
	v_pk_fma_f32 v[134:135], v[96:97], v[176:177], v[120:121]
	v_mul_f32_e32 v174, 0xbfb8aa3b, v172
	v_mul_f32_e32 v175, 0xbfb8aa3b, v173
	v_exp_f32_e32 v174, v174
	v_exp_f32_e32 v175, v175
	v_pk_fma_f32 v[170:171], v[170:171], v[110:111], v[126:127]
	v_pk_fma_f32 v[134:135], v[100:101], v[168:169], v[134:135]
	v_add_f32_e32 v174, 1.0, v174
	v_add_f32_e32 v175, 1.0, v175
	v_rcp_f32_e32 v174, v174
	v_rcp_f32_e32 v175, v175
	v_pk_fma_f32 v[170:171], v[162:163], v[114:115], v[170:171]
	v_pk_fma_f32 v[134:135], v[104:105], v[156:157], v[134:135]
	v_pk_fma_f32 v[170:171], v[138:139], v[118:119], v[170:171]
	v_pk_mul_f32 v[172:173], v[172:173], v[174:175]
	v_pk_fma_f32 v[132:133], v[102:103], v[166:167], v[132:133]
	v_pk_mul_f32 v[134:135], v[134:135], v[172:173]
	v_mul_f32_e32 v172, 0xbfb8aa3b, v170
	v_mul_f32_e32 v173, 0xbfb8aa3b, v171
	v_exp_f32_e32 v172, v172
	v_exp_f32_e32 v173, v173
	v_pk_fma_f32 v[132:133], v[106:107], v[146:147], v[132:133]
	v_cvt_pk_bf16_f32 v134, v134, v135
	v_add_f32_e32 v172, 1.0, v172
	v_add_f32_e32 v173, 1.0, v173
	v_rcp_f32_e32 v172, v172
	v_rcp_f32_e32 v173, v173
	v_pk_fma_f32 v[164:165], v[164:165], v[108:109], v[124:125]
	v_pk_fma_f32 v[162:163], v[162:163], v[110:111], v[126:127]
	v_pk_fma_f32 v[164:165], v[140:141], v[112:113], v[164:165]
	v_pk_mul_f32 v[170:171], v[170:171], v[172:173]
	v_pk_fma_f32 v[164:165], v[144:145], v[116:117], v[164:165]
	v_pk_mul_f32 v[132:133], v[132:133], v[170:171]
	v_add_u32_e32 v170, 3, v183
	v_cmp_gt_u32_e64 s[52:53], s89, v170
	v_add_u32_e32 v170, 0x6900, v182
	v_cvt_pk_bf16_f32 v135, v132, v133
	v_pk_fma_f32 v[132:133], v[98:99], v[166:167], v[122:123]
	v_pk_fma_f32 v[98:99], v[98:99], v[146:147], v[122:123]
	v_cndmask_b32_e64 v170, v137, v170, s[52:53]
	v_pk_fma_f32 v[132:133], v[102:103], v[146:147], v[132:133]
	v_pk_fma_f32 v[98:99], v[102:103], v[148:149], v[98:99]
	v_pk_fma_f32 v[102:103], v[140:141], v[108:109], v[124:125]
	global_store_dwordx2 v170, v[134:135], s[70:71]
	v_pk_fma_f32 v[134:135], v[96:97], v[168:169], v[120:121]
	v_pk_fma_f32 v[96:97], v[96:97], v[156:157], v[120:121]
	v_pk_fma_f32 v[102:103], v[144:145], v[112:113], v[102:103]
	v_pk_fma_f32 v[134:135], v[100:101], v[156:157], v[134:135]
	v_pk_fma_f32 v[96:97], v[100:101], v[160:161], v[96:97]
	v_pk_fma_f32 v[102:103], v[152:153], v[116:117], v[102:103]
	v_pk_fma_f32 v[134:135], v[104:105], v[160:161], v[134:135]
	v_mul_f32_e32 v166, 0xbfb8aa3b, v164
	v_mul_f32_e32 v167, 0xbfb8aa3b, v165
	v_pk_fma_f32 v[96:97], v[104:105], v[158:159], v[96:97]
	v_mul_f32_e32 v104, 0xbfb8aa3b, v102
	v_mul_f32_e32 v105, 0xbfb8aa3b, v103
	v_exp_f32_e32 v166, v166
	v_exp_f32_e32 v167, v167
	v_exp_f32_e32 v104, v104
	v_exp_f32_e32 v105, v105
	v_add_f32_e32 v166, 1.0, v166
	v_add_f32_e32 v167, 1.0, v167
	v_add_f32_e32 v104, 1.0, v104
	v_add_f32_e32 v105, 1.0, v105
	v_rcp_f32_e32 v166, v166
	v_rcp_f32_e32 v167, v167
	v_rcp_f32_e32 v104, v104
	v_rcp_f32_e32 v105, v105
	v_pk_fma_f32 v[100:101], v[138:139], v[110:111], v[126:127]
	v_pk_fma_f32 v[162:163], v[138:139], v[114:115], v[162:163]
	v_pk_fma_f32 v[100:101], v[142:143], v[114:115], v[100:101]
	v_pk_fma_f32 v[162:163], v[142:143], v[118:119], v[162:163]
	v_pk_mul_f32 v[164:165], v[164:165], v[166:167]
	v_pk_fma_f32 v[100:101], v[154:155], v[118:119], v[100:101]
	v_pk_mul_f32 v[102:103], v[102:103], v[104:105]
	v_pk_mul_f32 v[134:135], v[134:135], v[164:165]
	v_mul_f32_e32 v164, 0xbfb8aa3b, v162
	v_mul_f32_e32 v165, 0xbfb8aa3b, v163
	v_pk_mul_f32 v[96:97], v[96:97], v[102:103]
	v_mul_f32_e32 v102, 0xbfb8aa3b, v100
	v_mul_f32_e32 v103, 0xbfb8aa3b, v101
	v_exp_f32_e32 v164, v164
	v_exp_f32_e32 v165, v165
	v_exp_f32_e32 v102, v102
	v_exp_f32_e32 v103, v103
	v_add_f32_e32 v164, 1.0, v164
	v_add_f32_e32 v165, 1.0, v165
	v_add_f32_e32 v102, 1.0, v102
	v_add_f32_e32 v103, 1.0, v103
	v_rcp_f32_e32 v164, v164
	v_rcp_f32_e32 v165, v165
	v_rcp_f32_e32 v102, v102
	v_rcp_f32_e32 v103, v103
	v_pk_fma_f32 v[132:133], v[106:107], v[148:149], v[132:133]
	v_pk_mul_f32 v[162:163], v[162:163], v[164:165]
	v_pk_fma_f32 v[98:99], v[106:107], v[150:151], v[98:99]
	v_pk_mul_f32 v[100:101], v[100:101], v[102:103]
	v_pk_mul_f32 v[132:133], v[132:133], v[162:163]
	v_add_u32_e32 v162, 4, v183
	v_pk_mul_f32 v[98:99], v[98:99], v[100:101]
	v_add_u32_e32 v100, 5, v183
	v_cmp_gt_u32_e64 s[54:55], s89, v162
	v_add_u32_e32 v162, 0x7e00, v182
	v_cmp_gt_u32_e64 s[56:57], s89, v100
	v_add_u32_e32 v100, 0x9300, v182
	v_cndmask_b32_e64 v162, v137, v162, s[54:55]
	v_cvt_pk_bf16_f32 v134, v134, v135
	v_cvt_pk_bf16_f32 v135, v132, v133
	v_cndmask_b32_e64 v100, v137, v100, s[56:57]
	v_cvt_pk_bf16_f32 v96, v96, v97
	v_cvt_pk_bf16_f32 v97, v98, v99
	global_store_dwordx2 v162, v[134:135], s[70:71]
	global_store_dwordx2 v100, v[96:97], s[70:71]
	v_pk_mul_f32 v[106:107], v[56:57], s[38:39] op_sel_hi:[1,0]
	v_pk_mul_f32 v[100:101], v[46:47], s[38:39] op_sel_hi:[1,0]
	v_pk_mul_f32 v[56:57], v[92:93], s[38:39] op_sel_hi:[1,0]
	v_pk_mul_f32 v[46:47], v[84:85], s[38:39] op_sel_hi:[1,0]
	v_pk_mul_f32 v[108:109], v[54:55], s[38:39] op_sel_hi:[1,0]
	v_pk_mul_f32 v[54:55], v[94:95], s[38:39] op_sel_hi:[1,0]
	v_pk_mul_f32 v[84:85], v[2:3], s[38:39] op_sel_hi:[1,0]
	v_pk_mul_f32 v[2:3], v[80:81], s[38:39] op_sel_hi:[1,0]
	v_mov_b32_dpp v92, v46 row_shr:1 row_mask:0xf bank_mask:0xf bound_ctrl:1
	v_mov_b32_dpp v93, v47 row_shr:1 row_mask:0xf bank_mask:0xf bound_ctrl:1
	v_mov_b32_dpp v94, v2 row_shr:1 row_mask:0xf bank_mask:0xf bound_ctrl:1
	s_waitcnt vmcnt(0)
	v_pk_fma_f32 v[92:93], v[24:25], v[92:93], v[60:61]
	v_mov_b32_dpp v95, v3 row_shr:1 row_mask:0xf bank_mask:0xf bound_ctrl:1
	v_pk_mul_f32 v[96:97], v[42:43], s[38:39] op_sel_hi:[1,0]
	v_pk_mul_f32 v[42:43], v[88:89], s[38:39] op_sel_hi:[1,0]
	v_pk_mul_f32 v[88:89], v[0:1], s[38:39] op_sel_hi:[1,0]
	v_pk_mul_f32 v[0:1], v[82:83], s[38:39] op_sel_hi:[1,0]
	v_cndmask_b32_e64 v83, v107, 0, s[44:45]
	v_cndmask_b32_e64 v82, v106, 0, s[44:45]
	v_pk_fma_f32 v[92:93], v[36:37], v[94:95], v[92:93]
	v_pk_mul_f32 v[102:103], v[44:45], s[38:39] op_sel_hi:[1,0]
	v_pk_fma_f32 v[92:93], v[82:83], v[48:49], v[92:93]
	v_pk_mul_f32 v[44:45], v[86:87], s[38:39] op_sel_hi:[1,0]
	v_mul_f32_e32 v112, 0xbfb8aa3b, v92
	v_mul_f32_e32 v113, 0xbfb8aa3b, v93
	v_exp_f32_e32 v112, v112
	v_exp_f32_e32 v113, v113
	v_pk_mul_f32 v[86:87], v[6:7], s[38:39] op_sel_hi:[1,0]
	v_pk_mul_f32 v[104:105], v[58:59], s[38:39] op_sel_hi:[1,0]
	v_add_f32_e32 v112, 1.0, v112
	v_add_f32_e32 v113, 1.0, v113
	v_pk_mul_f32 v[110:111], v[52:53], s[38:39] op_sel_hi:[1,0]
	v_pk_mul_f32 v[52:53], v[78:79], s[38:39] op_sel_hi:[1,0]
	v_pk_mul_f32 v[58:59], v[66:67], s[38:39] op_sel_hi:[1,0]
	v_pk_mul_f32 v[66:67], v[14:15], s[38:39] op_sel_hi:[1,0]
	v_pk_mul_f32 v[78:79], v[10:11], s[38:39] op_sel_hi:[1,0]
	v_pk_mul_f32 v[10:11], v[70:71], s[38:39] op_sel_hi:[1,0]
	v_pk_mul_f32 v[14:15], v[74:75], s[38:39] op_sel_hi:[1,0]
	v_pk_mul_f32 v[6:7], v[76:77], s[38:39] op_sel_hi:[1,0]
	v_pk_mul_f32 v[70:71], v[12:13], s[38:39] op_sel_hi:[1,0]
	v_pk_mul_f32 v[74:75], v[8:9], s[38:39] op_sel_hi:[1,0]
	v_pk_mul_f32 v[12:13], v[68:69], s[38:39] op_sel_hi:[1,0]
	v_pk_mul_f32 v[8:9], v[72:73], s[38:39] op_sel_hi:[1,0]
	v_pk_mul_f32 v[76:77], v[4:5], s[38:39] op_sel_hi:[1,0]
	v_cndmask_b32_e64 v5, v109, 0, s[44:45]
	v_cndmask_b32_e64 v4, v108, 0, s[44:45]
	v_cndmask_b32_e64 v73, v87, 0, s[44:45]
	v_cndmask_b32_e64 v72, v86, 0, s[44:45]
	v_cndmask_b32_e64 v87, v89, 0, s[44:45]
	v_cndmask_b32_e64 v86, v88, 0, s[44:45]
	v_rcp_f32_e32 v112, v112
	v_rcp_f32_e32 v113, v113
	v_pk_mul_f32 v[98:99], v[40:41], s[38:39] op_sel_hi:[1,0]
	v_pk_mul_f32 v[40:41], v[90:91], s[38:39] op_sel_hi:[1,0]
	v_cndmask_b32_e64 v69, v111, 0, s[44:45]
	v_cndmask_b32_e64 v68, v110, 0, s[44:45]
	v_mov_b32_dpp v88, v12 row_shr:1 row_mask:0xf bank_mask:0xf bound_ctrl:1
	v_mov_b32_dpp v89, v13 row_shr:1 row_mask:0xf bank_mask:0xf bound_ctrl:1
	v_mov_b32_dpp v108, v44 row_shr:1 row_mask:0xf bank_mask:0xf bound_ctrl:1
	v_mov_b32_dpp v109, v45 row_shr:1 row_mask:0xf bank_mask:0xf bound_ctrl:1
	v_mov_b32_dpp v90, v8 row_shr:1 row_mask:0xf bank_mask:0xf bound_ctrl:1
	v_mov_b32_dpp v91, v9 row_shr:1 row_mask:0xf bank_mask:0xf bound_ctrl:1
	v_mov_b32_dpp v110, v0 row_shr:1 row_mask:0xf bank_mask:0xf bound_ctrl:1
	v_mov_b32_dpp v111, v1 row_shr:1 row_mask:0xf bank_mask:0xf bound_ctrl:1
	v_pk_fma_f32 v[88:89], v[16:17], v[88:89], v[32:33]
	v_pk_fma_f32 v[108:109], v[26:27], v[108:109], v[62:63]
	v_cndmask_b32_e64 v81, v105, 0, s[44:45]
	v_cndmask_b32_e64 v80, v104, 0, s[44:45]
	v_pk_fma_f32 v[88:89], v[20:21], v[90:91], v[88:89]
	v_pk_fma_f32 v[108:109], v[38:39], v[110:111], v[108:109]
	v_pk_fma_f32 v[88:89], v[86:87], v[28:29], v[88:89]
	v_pk_fma_f32 v[108:109], v[80:81], v[50:51], v[108:109]
	v_pk_mul_f32 v[92:93], v[92:93], v[112:113]
	v_pk_mul_f32 v[88:89], v[88:89], v[92:93]
	v_mul_f32_e32 v92, 0xbfb8aa3b, v108
	v_mul_f32_e32 v93, 0xbfb8aa3b, v109
	v_exp_f32_e32 v92, v92
	v_exp_f32_e32 v93, v93
	v_mov_b32_dpp v104, v10 row_shr:1 row_mask:0xf bank_mask:0xf bound_ctrl:1
	v_add_f32_e32 v92, 1.0, v92
	v_add_f32_e32 v93, 1.0, v93
	v_rcp_f32_e32 v92, v92
	v_rcp_f32_e32 v93, v93
	v_mov_b32_dpp v105, v11 row_shr:1 row_mask:0xf bank_mask:0xf bound_ctrl:1
	v_mov_b32_dpp v106, v14 row_shr:1 row_mask:0xf bank_mask:0xf bound_ctrl:1
	v_pk_fma_f32 v[104:105], v[18:19], v[104:105], v[34:35]
	v_mov_b32_dpp v107, v15 row_shr:1 row_mask:0xf bank_mask:0xf bound_ctrl:1
	v_cndmask_b32_e64 v85, v85, 0, s[44:45]
	v_cndmask_b32_e64 v84, v84, 0, s[44:45]
	v_pk_fma_f32 v[104:105], v[22:23], v[106:107], v[104:105]
	v_or_b32_e32 v114, 4, v136
	v_pk_fma_f32 v[104:105], v[84:85], v[30:31], v[104:105]
	v_pk_mul_f32 v[92:93], v[108:109], v[92:93]
	v_pk_fma_f32 v[94:95], v[24:25], v[94:95], v[60:61]
	v_pk_mul_f32 v[92:93], v[104:105], v[92:93]
	v_add_lshl_u32 v104, v184, v114, 1
	v_pk_fma_f32 v[94:95], v[82:83], v[36:37], v[94:95]
	v_cndmask_b32_e64 v104, v137, v104, s[46:47]
	v_cvt_pk_bf16_f32 v88, v88, v89
	v_cvt_pk_bf16_f32 v89, v92, v93
	v_pk_fma_f32 v[94:95], v[68:69], v[48:49], v[94:95]
	global_store_dwordx2 v104, v[88:89], s[70:71]
	v_mul_f32_e32 v104, 0xbfb8aa3b, v94
	v_mul_f32_e32 v105, 0xbfb8aa3b, v95
	v_exp_f32_e32 v104, v104
	v_exp_f32_e32 v105, v105
	v_pk_fma_f32 v[90:91], v[16:17], v[90:91], v[32:33]
	v_pk_fma_f32 v[92:93], v[26:27], v[110:111], v[62:63]
	v_add_f32_e32 v104, 1.0, v104
	v_add_f32_e32 v105, 1.0, v105
	v_rcp_f32_e32 v104, v104
	v_rcp_f32_e32 v105, v105
	v_cndmask_b32_e64 v77, v77, 0, s[44:45]
	v_cndmask_b32_e64 v76, v76, 0, s[44:45]
	v_pk_fma_f32 v[90:91], v[86:87], v[20:21], v[90:91]
	v_pk_fma_f32 v[92:93], v[80:81], v[38:39], v[92:93]
	v_pk_fma_f32 v[90:91], v[76:77], v[28:29], v[90:91]
	v_pk_fma_f32 v[92:93], v[4:5], v[50:51], v[92:93]
	v_pk_mul_f32 v[94:95], v[94:95], v[104:105]
	v_pk_fma_f32 v[88:89], v[18:19], v[106:107], v[34:35]
	v_pk_mul_f32 v[90:91], v[90:91], v[94:95]
	v_mul_f32_e32 v94, 0xbfb8aa3b, v92
	v_mul_f32_e32 v95, 0xbfb8aa3b, v93
	v_exp_f32_e32 v94, v94
	v_exp_f32_e32 v95, v95
	v_pk_fma_f32 v[88:89], v[84:85], v[22:23], v[88:89]
	v_pk_fma_f32 v[82:83], v[82:83], v[24:25], v[60:61]
	v_add_f32_e32 v94, 1.0, v94
	v_add_f32_e32 v95, 1.0, v95
	v_rcp_f32_e32 v94, v94
	v_rcp_f32_e32 v95, v95
	v_pk_fma_f32 v[88:89], v[72:73], v[30:31], v[88:89]
	v_pk_fma_f32 v[82:83], v[68:69], v[36:37], v[82:83]
	v_cvt_pk_bf16_f32 v90, v90, v91
	v_pk_mul_f32 v[92:93], v[92:93], v[94:95]
	v_pk_fma_f32 v[82:83], v[102:103], v[48:49], v[82:83]
	v_pk_mul_f32 v[88:89], v[88:89], v[92:93]
	v_pk_fma_f32 v[86:87], v[86:87], v[16:17], v[32:33]
	v_cvt_pk_bf16_f32 v91, v88, v89
	v_mul_f32_e32 v88, 0xbfb8aa3b, v82
	v_mul_f32_e32 v89, 0xbfb8aa3b, v83
	v_exp_f32_e32 v88, v88
	v_exp_f32_e32 v89, v89
	v_pk_fma_f32 v[80:81], v[80:81], v[26:27], v[62:63]
	v_pk_fma_f32 v[86:87], v[76:77], v[20:21], v[86:87]
	v_add_f32_e32 v88, 1.0, v88
	v_add_f32_e32 v89, 1.0, v89
	v_rcp_f32_e32 v88, v88
	v_rcp_f32_e32 v89, v89
	v_pk_fma_f32 v[80:81], v[4:5], v[38:39], v[80:81]
	v_pk_fma_f32 v[86:87], v[74:75], v[28:29], v[86:87]
	v_pk_fma_f32 v[80:81], v[100:101], v[50:51], v[80:81]
	v_pk_mul_f32 v[82:83], v[82:83], v[88:89]
	v_pk_fma_f32 v[84:85], v[84:85], v[18:19], v[34:35]
	v_pk_mul_f32 v[82:83], v[86:87], v[82:83]
	v_mul_f32_e32 v86, 0xbfb8aa3b, v80
	v_mul_f32_e32 v87, 0xbfb8aa3b, v81
	v_exp_f32_e32 v86, v86
	v_exp_f32_e32 v87, v87
	v_pk_fma_f32 v[84:85], v[72:73], v[22:23], v[84:85]
	v_pk_fma_f32 v[68:69], v[68:69], v[24:25], v[60:61]
	v_add_f32_e32 v86, 1.0, v86
	v_add_f32_e32 v87, 1.0, v87
	v_rcp_f32_e32 v86, v86
	v_rcp_f32_e32 v87, v87
	v_pk_fma_f32 v[84:85], v[78:79], v[30:31], v[84:85]
	v_pk_fma_f32 v[68:69], v[102:103], v[36:37], v[68:69]
	v_cvt_pk_bf16_f32 v82, v82, v83
	v_pk_mul_f32 v[80:81], v[80:81], v[86:87]
	v_pk_fma_f32 v[68:69], v[98:99], v[48:49], v[68:69]
	v_pk_mul_f32 v[80:81], v[84:85], v[80:81]
	v_pk_fma_f32 v[76:77], v[76:77], v[16:17], v[32:33]
	v_cvt_pk_bf16_f32 v83, v80, v81
	v_mul_f32_e32 v80, 0xbfb8aa3b, v68
	v_mul_f32_e32 v81, 0xbfb8aa3b, v69
	v_exp_f32_e32 v80, v80
	v_exp_f32_e32 v81, v81
	v_pk_fma_f32 v[4:5], v[4:5], v[26:27], v[62:63]
	v_pk_fma_f32 v[76:77], v[74:75], v[20:21], v[76:77]
	v_add_f32_e32 v80, 1.0, v80
	v_add_f32_e32 v81, 1.0, v81
	v_rcp_f32_e32 v80, v80
	v_rcp_f32_e32 v81, v81
	v_pk_fma_f32 v[4:5], v[100:101], v[38:39], v[4:5]
	v_pk_fma_f32 v[76:77], v[70:71], v[28:29], v[76:77]
	v_pk_fma_f32 v[4:5], v[96:97], v[50:51], v[4:5]
	v_pk_mul_f32 v[68:69], v[68:69], v[80:81]
	v_pk_fma_f32 v[72:73], v[72:73], v[18:19], v[34:35]
	v_pk_mul_f32 v[68:69], v[76:77], v[68:69]
	v_mul_f32_e32 v76, 0xbfb8aa3b, v4
	v_mul_f32_e32 v77, 0xbfb8aa3b, v5
	v_exp_f32_e32 v76, v76
	v_exp_f32_e32 v77, v77
	v_pk_fma_f32 v[72:73], v[78:79], v[22:23], v[72:73]
	v_add_u32_e32 v92, 0x1508, v182
	v_add_f32_e32 v76, 1.0, v76
	v_add_f32_e32 v77, 1.0, v77
	v_rcp_f32_e32 v76, v76
	v_rcp_f32_e32 v77, v77
	v_pk_fma_f32 v[72:73], v[66:67], v[30:31], v[72:73]
	v_add_lshl_u32 v84, v185, v114, 1
	v_cndmask_b32_e64 v92, v137, v92, s[48:49]
	v_pk_mul_f32 v[4:5], v[4:5], v[76:77]
	v_cndmask_b32_e32 v84, v137, v84, vcc
	v_pk_mul_f32 v[4:5], v[72:73], v[4:5]
	v_add_u32_e32 v72, 0x3f08, v182
	v_cndmask_b32_e32 v72, v137, v72, vcc
	v_cvt_pk_bf16_f32 v68, v68, v69
	v_cvt_pk_bf16_f32 v69, v4, v5
	global_store_dwordx2 v92, v[90:91], s[70:71]
	global_store_dwordx2 v84, v[82:83], s[70:71]
	global_store_dwordx2 v72, v[68:69], s[70:71]
	v_pk_fma_f32 v[68:69], v[74:75], v[16:17], v[32:33]
	v_pk_fma_f32 v[74:75], v[102:103], v[24:25], v[60:61]
	v_pk_fma_f32 v[72:73], v[100:101], v[26:27], v[62:63]
	v_pk_fma_f32 v[74:75], v[98:99], v[36:37], v[74:75]
	v_pk_mul_f32 v[64:65], v[64:65], s[38:39] op_sel_hi:[1,0]
	v_pk_fma_f32 v[74:75], v[56:57], v[48:49], v[74:75]
	v_pk_fma_f32 v[68:69], v[70:71], v[20:21], v[68:69]
	v_mul_f32_e32 v76, 0xbfb8aa3b, v74
	v_mul_f32_e32 v77, 0xbfb8aa3b, v75
	v_exp_f32_e32 v76, v76
	v_exp_f32_e32 v77, v77
	v_pk_fma_f32 v[72:73], v[96:97], v[38:39], v[72:73]
	v_pk_fma_f32 v[68:69], v[64:65], v[28:29], v[68:69]
	v_add_f32_e32 v76, 1.0, v76
	v_add_f32_e32 v77, 1.0, v77
	v_rcp_f32_e32 v76, v76
	v_rcp_f32_e32 v77, v77
	v_pk_fma_f32 v[72:73], v[54:55], v[50:51], v[72:73]
	v_pk_fma_f32 v[4:5], v[78:79], v[18:19], v[34:35]
	s_add_i32 s7, s7, s10
	v_pk_mul_f32 v[74:75], v[74:75], v[76:77]
	v_pk_fma_f32 v[4:5], v[66:67], v[22:23], v[4:5]
	v_pk_mul_f32 v[68:69], v[68:69], v[74:75]
	v_mul_f32_e32 v74, 0xbfb8aa3b, v72
	v_mul_f32_e32 v75, 0xbfb8aa3b, v73
	v_exp_f32_e32 v74, v74
	v_exp_f32_e32 v75, v75
	v_pk_fma_f32 v[4:5], v[58:59], v[30:31], v[4:5]
	v_cvt_pk_bf16_f32 v68, v68, v69
	v_add_f32_e32 v74, 1.0, v74
	v_add_f32_e32 v75, 1.0, v75
	v_rcp_f32_e32 v74, v74
	v_rcp_f32_e32 v75, v75
	s_andn2_b64 vcc, exec, s[42:43]
	s_mov_b32 s46, s0
	s_mov_b32 s9, s8
	v_pk_mul_f32 v[72:73], v[72:73], v[74:75]
	s_mov_b64 s[18:19], s[16:17]
	v_pk_mul_f32 v[4:5], v[4:5], v[72:73]
	v_add_u32_e32 v72, 0x5408, v182
	v_cvt_pk_bf16_f32 v69, v4, v5
	v_pk_fma_f32 v[4:5], v[66:67], v[18:19], v[34:35]
	v_pk_fma_f32 v[66:67], v[70:71], v[16:17], v[32:33]
	v_pk_fma_f32 v[70:71], v[98:99], v[24:25], v[60:61]
	v_cndmask_b32_e64 v72, v137, v72, s[50:51]
	v_pk_fma_f32 v[70:71], v[56:57], v[36:37], v[70:71]
	global_store_dwordx2 v72, v[68:69], s[70:71]
	v_pk_fma_f32 v[70:71], v[42:43], v[48:49], v[70:71]
	v_pk_fma_f32 v[68:69], v[96:97], v[26:27], v[62:63]
	v_mul_f32_e32 v72, 0xbfb8aa3b, v70
	v_mul_f32_e32 v73, 0xbfb8aa3b, v71
	v_exp_f32_e32 v72, v72
	v_exp_f32_e32 v73, v73
	v_pk_fma_f32 v[66:67], v[64:65], v[20:21], v[66:67]
	v_pk_fma_f32 v[68:69], v[54:55], v[38:39], v[68:69]
	v_add_f32_e32 v72, 1.0, v72
	v_add_f32_e32 v73, 1.0, v73
	v_rcp_f32_e32 v72, v72
	v_rcp_f32_e32 v73, v73
	v_pk_fma_f32 v[66:67], v[6:7], v[28:29], v[66:67]
	v_pk_fma_f32 v[68:69], v[40:41], v[50:51], v[68:69]
	v_pk_fma_f32 v[4:5], v[58:59], v[22:23], v[4:5]
	v_pk_mul_f32 v[70:71], v[70:71], v[72:73]
	v_pk_fma_f32 v[56:57], v[56:57], v[24:25], v[60:61]
	v_pk_mul_f32 v[66:67], v[66:67], v[70:71]
	v_mul_f32_e32 v70, 0xbfb8aa3b, v68
	v_mul_f32_e32 v71, 0xbfb8aa3b, v69
	v_exp_f32_e32 v70, v70
	v_exp_f32_e32 v71, v71
	v_pk_fma_f32 v[4:5], v[52:53], v[30:31], v[4:5]
	v_pk_fma_f32 v[56:57], v[42:43], v[36:37], v[56:57]
	v_add_f32_e32 v70, 1.0, v70
	v_add_f32_e32 v71, 1.0, v71
	v_rcp_f32_e32 v70, v70
	v_rcp_f32_e32 v71, v71
	v_pk_fma_f32 v[56:57], v[46:47], v[48:49], v[56:57]
	v_cvt_pk_bf16_f32 v66, v66, v67
	v_pk_fma_f32 v[54:55], v[54:55], v[26:27], v[62:63]
	v_pk_mul_f32 v[68:69], v[68:69], v[70:71]
	v_pk_fma_f32 v[54:55], v[40:41], v[38:39], v[54:55]
	v_pk_mul_f32 v[4:5], v[4:5], v[68:69]
	v_pk_fma_f32 v[54:55], v[44:45], v[50:51], v[54:55]
	v_cvt_pk_bf16_f32 v67, v4, v5
	v_pk_fma_f32 v[4:5], v[58:59], v[18:19], v[34:35]
	v_pk_fma_f32 v[58:59], v[64:65], v[16:17], v[32:33]
	v_mul_f32_e32 v64, 0xbfb8aa3b, v56
	v_mul_f32_e32 v65, 0xbfb8aa3b, v57
	v_exp_f32_e32 v64, v64
	v_exp_f32_e32 v65, v65
	v_pk_fma_f32 v[58:59], v[6:7], v[20:21], v[58:59]
	v_pk_fma_f32 v[6:7], v[6:7], v[16:17], v[32:33]
	v_add_f32_e32 v64, 1.0, v64
	v_add_f32_e32 v65, 1.0, v65
	v_rcp_f32_e32 v64, v64
	v_rcp_f32_e32 v65, v65
	v_pk_fma_f32 v[6:7], v[12:13], v[20:21], v[6:7]
	v_pk_fma_f32 v[58:59], v[12:13], v[28:29], v[58:59]
	v_pk_fma_f32 v[6:7], v[8:9], v[28:29], v[6:7]
	v_pk_fma_f32 v[8:9], v[40:41], v[26:27], v[62:63]
	v_pk_mul_f32 v[56:57], v[56:57], v[64:65]
	v_pk_fma_f32 v[8:9], v[44:45], v[38:39], v[8:9]
	v_pk_mul_f32 v[56:57], v[58:59], v[56:57]
	v_pk_fma_f32 v[0:1], v[0:1], v[50:51], v[8:9]
	v_mul_f32_e32 v58, 0xbfb8aa3b, v54
	v_mul_f32_e32 v59, 0xbfb8aa3b, v55
	v_mul_f32_e32 v8, 0xbfb8aa3b, v1
	v_exp_f32_e32 v58, v58
	v_exp_f32_e32 v59, v59
	v_exp_f32_e32 v8, v8
	v_pk_fma_f32 v[4:5], v[52:53], v[22:23], v[4:5]
	v_add_f32_e32 v58, 1.0, v58
	v_add_f32_e32 v59, 1.0, v59
	v_add_f32_e32 v8, 1.0, v8
	v_rcp_f32_e32 v58, v58
	v_rcp_f32_e32 v59, v59
	v_rcp_f32_e32 v9, v8
	v_mul_f32_e32 v8, 0xbfb8aa3b, v0
	v_exp_f32_e32 v8, v8
	v_pk_fma_f32 v[4:5], v[10:11], v[30:31], v[4:5]
	v_pk_mul_f32 v[54:55], v[54:55], v[58:59]
	v_add_u32_e32 v68, 0x6908, v182
	v_pk_mul_f32 v[4:5], v[4:5], v[54:55]
	v_add_u32_e32 v54, 0x7e08, v182
	v_add_f32_e32 v8, 1.0, v8
	v_cndmask_b32_e64 v68, v137, v68, s[52:53]
	v_cndmask_b32_e64 v58, v137, v54, s[54:55]
	v_cvt_pk_bf16_f32 v54, v56, v57
	v_cvt_pk_bf16_f32 v55, v4, v5
	v_add_u32_e32 v4, 0x9308, v182
	v_rcp_f32_e32 v8, v8
	global_store_dwordx2 v68, v[66:67], s[70:71]
	global_store_dwordx2 v58, v[54:55], s[70:71]
	v_cndmask_b32_e64 v54, v137, v4, s[56:57]
	v_pk_fma_f32 v[4:5], v[52:53], v[18:19], v[34:35]
	v_pk_mul_f32 v[0:1], v[0:1], v[8:9]
	v_pk_fma_f32 v[4:5], v[10:11], v[22:23], v[4:5]
	v_pk_fma_f32 v[10:11], v[42:43], v[24:25], v[60:61]
	v_pk_fma_f32 v[4:5], v[14:15], v[30:31], v[4:5]
	v_pk_fma_f32 v[10:11], v[46:47], v[36:37], v[10:11]
	v_pk_mul_f32 v[0:1], v[4:5], v[0:1]
	v_pk_fma_f32 v[2:3], v[2:3], v[48:49], v[10:11]
	s_mov_b64 s[20:21], s[14:15]
	v_mul_f32_e32 v4, 0xbfb8aa3b, v3
	v_exp_f32_e32 v4, v4
	s_nop 0
	v_add_f32_e32 v4, 1.0, v4
	v_rcp_f32_e32 v5, v4
	v_mul_f32_e32 v4, 0xbfb8aa3b, v2
	v_exp_f32_e32 v4, v4
	s_nop 0
	v_add_f32_e32 v4, 1.0, v4
	v_rcp_f32_e32 v4, v4
	s_nop 0
	v_pk_mul_f32 v[2:3], v[2:3], v[4:5]
	s_nop 0
	v_pk_mul_f32 v[2:3], v[6:7], v[2:3]
	s_nop 0
	v_cvt_pk_bf16_f32 v2, v2, v3
	v_cvt_pk_bf16_f32 v3, v0, v1
	global_store_dwordx2 v54, v[2:3], s[70:71]
	s_cbranch_vccz .LBB0_2082

.LBB0_2104:
	s_or_b64 exec, exec, s[2:3]
	s_mov_b32 s2, 0xa800
	v_mad_i64_i32 v[184:185], s[2:3], v186, s2, 0
	v_cmp_ne_u32_e64 s[42:43], 0, v128
	v_cmp_eq_u32_e64 s[44:45], 0, v128
	v_lshl_add_u64 v[188:189], s[10:11], 0, v[184:185]
	v_mov_b32_dpp v172, v80 row_shr:1 row_mask:0xf bank_mask:0xf bound_ctrl:1
	v_mov_b32_dpp v132, v76 row_shr:1 row_mask:0xf bank_mask:0xf bound_ctrl:1
	v_mov_b32_dpp v168, v68 row_shr:1 row_mask:0xf bank_mask:0xf bound_ctrl:1
	v_mov_b32_dpp v128, v64 row_shr:1 row_mask:0xf bank_mask:0xf bound_ctrl:1
	v_mov_b32_dpp v173, v81 row_shr:1 row_mask:0xf bank_mask:0xf bound_ctrl:1
	v_mov_b32_dpp v133, v77 row_shr:1 row_mask:0xf bank_mask:0xf bound_ctrl:1
	v_mov_b32_dpp v169, v69 row_shr:1 row_mask:0xf bank_mask:0xf bound_ctrl:1
	v_mov_b32_dpp v129, v65 row_shr:1 row_mask:0xf bank_mask:0xf bound_ctrl:1
	v_mov_b32_dpp v174, v82 row_shr:1 row_mask:0xf bank_mask:0xf bound_ctrl:1
	v_mov_b32_dpp v134, v78 row_shr:1 row_mask:0xf bank_mask:0xf bound_ctrl:1
	v_mov_b32_dpp v170, v70 row_shr:1 row_mask:0xf bank_mask:0xf bound_ctrl:1
	v_mov_b32_dpp v130, v66 row_shr:1 row_mask:0xf bank_mask:0xf bound_ctrl:1
	v_mov_b32_dpp v175, v83 row_shr:1 row_mask:0xf bank_mask:0xf bound_ctrl:1
	v_mov_b32_dpp v135, v79 row_shr:1 row_mask:0xf bank_mask:0xf bound_ctrl:1
	v_mov_b32_dpp v171, v71 row_shr:1 row_mask:0xf bank_mask:0xf bound_ctrl:1
	v_mov_b32_dpp v131, v67 row_shr:1 row_mask:0xf bank_mask:0xf bound_ctrl:1
	v_lshl_add_u64 v[184:185], v[188:189], 0, s[46:47]
	s_and_saveexec_b64 s[2:3], s[44:45]
	s_cbranch_execz .LBB0_2106
	v_lshlrev_b64 v[128:129], 2, v[200:201]
	v_lshl_add_u64 v[130:131], v[184:185], 0, v[128:129]
	v_lshl_add_u64 v[128:129], v[188:189], 0, v[128:129]
	v_lshl_add_u64 v[132:133], v[184:185], 0, v[194:195]
	v_lshl_add_u64 v[134:135], v[188:189], 0, v[194:195]
	global_load_dwordx4 v[172:175], v[134:135], off
	s_nop 0
	global_load_dwordx4 v[132:135], v[132:133], off
	s_nop 0
	global_load_dwordx4 v[168:171], v[128:129], off
	s_nop 0
	global_load_dwordx4 v[128:131], v[130:131], off

.LBB0_2108:
	s_or_b64 exec, exec, s[2:3]
	v_mov_b32_dpp v76, v16 row_shr:1 row_mask:0xf bank_mask:0xf bound_ctrl:1
	v_mov_b32_dpp v64, v12 row_shr:1 row_mask:0xf bank_mask:0xf bound_ctrl:1
	v_mov_b32_dpp v72, v4 row_shr:1 row_mask:0xf bank_mask:0xf bound_ctrl:1
	v_mov_b32_dpp v68, v0 row_shr:1 row_mask:0xf bank_mask:0xf bound_ctrl:1
	v_mov_b32_dpp v77, v17 row_shr:1 row_mask:0xf bank_mask:0xf bound_ctrl:1
	v_mov_b32_dpp v65, v13 row_shr:1 row_mask:0xf bank_mask:0xf bound_ctrl:1
	v_mov_b32_dpp v73, v5 row_shr:1 row_mask:0xf bank_mask:0xf bound_ctrl:1
	v_mov_b32_dpp v69, v1 row_shr:1 row_mask:0xf bank_mask:0xf bound_ctrl:1
	v_mov_b32_dpp v78, v18 row_shr:1 row_mask:0xf bank_mask:0xf bound_ctrl:1
	v_mov_b32_dpp v66, v14 row_shr:1 row_mask:0xf bank_mask:0xf bound_ctrl:1
	v_mov_b32_dpp v74, v6 row_shr:1 row_mask:0xf bank_mask:0xf bound_ctrl:1
	v_mov_b32_dpp v70, v2 row_shr:1 row_mask:0xf bank_mask:0xf bound_ctrl:1
	v_mov_b32_dpp v79, v19 row_shr:1 row_mask:0xf bank_mask:0xf bound_ctrl:1
	v_mov_b32_dpp v67, v15 row_shr:1 row_mask:0xf bank_mask:0xf bound_ctrl:1
	v_mov_b32_dpp v75, v7 row_shr:1 row_mask:0xf bank_mask:0xf bound_ctrl:1
	v_mov_b32_dpp v71, v3 row_shr:1 row_mask:0xf bank_mask:0xf bound_ctrl:1
	s_and_saveexec_b64 s[2:3], s[42:43]
	s_xor_b64 s[2:3], exec, s[2:3]
	s_andn2_saveexec_b64 s[2:3], s[2:3]
	s_cbranch_execz .LBB0_2093
	v_lshl_add_u64 v[68:69], v[182:183], 2, v[188:189]
	v_lshl_add_u64 v[64:65], v[82:83], 2, v[184:185]
	global_load_dwordx4 v[76:79], v[68:69], off offset:16
	s_nop 0
	global_load_dwordx4 v[64:67], v[64:65], off
	v_add_co_u32_e32 v68, vcc, 0x2000, v68
	v_lshl_add_u64 v[70:71], v[84:85], 2, v[184:185]
	s_nop 0
	v_addc_co_u32_e32 v69, vcc, 0, v69, vcc
	global_load_dwordx4 v[72:75], v[68:69], off offset:2576
	s_nop 0
	global_load_dwordx4 v[68:71], v[70:71], off
	s_branch .LBB0_2093
